# residual-add GEMM epilogues (MLP2, A-out, C-out) rewritten by hand: all 32 residual loads issued up front into free/drained accumulator registers, counted vmcnt (no per-row load+vmcnt(0) that also dra
# speedup vs baseline: 1.0238x; 1.0238x over previous
.LBB0_1141:
	v_readfirstlane_b32 s40, v204
	s_lshr_b32 s40, s40, 6
	s_and_b32 s41, s40, 1
	s_bfe_u32 s42, s40, 0x10001
	s_lshr_b32 s43, s40, 2
	s_lshl_b32 s44, s4, 1
	s_add_i32 s44, s44, s42
	s_lshl_b32 s45, s44, 7
	s_lshl_b32 s46, s41, 6
	s_add_i32 s45, s45, s46
	s_lshl_b32 s46, s43, 7
	s_add_i32 s46, s46, s2
	s_lshl_b32 s47, s44, 1
	s_add_i32 s47, s47, s41
	v_readlane_b32 s36, v251, 50
	v_readlane_b32 s37, v251, 51
	v_readlane_b32 s38, v250, 9
	v_readlane_b32 s39, v250, 10
	v_readlane_b32 s50, v250, 11
	v_readlane_b32 s51, v250, 12
	s_add_u32 s34, s50, 0xf900000
	s_addc_u32 s35, s51, 0
	s_add_u32 s50, s50, 0x5800000
	s_addc_u32 s51, s51, 0
	s_lshl_b32 s48, s46, 12
	s_lshl_b32 s49, s45, 2
	s_add_u32 s48, s48, s49
	s_add_u32 s36, s36, s48
	s_addc_u32 s37, s37, 0
	s_add_u32 s38, s38, s48
	s_addc_u32 s39, s39, 0
	s_lshr_b32 s48, s48, 1
	s_add_u32 s50, s50, s48
	s_addc_u32 s51, s51, 0
	s_lshl_b32 s48, s46, 6
	s_lshl_b32 s49, s47, 2
	s_add_u32 s48, s48, s49
	s_add_u32 s34, s34, s48
	s_addc_u32 s35, s35, 0
	v_and_b32_e32 v249, 63, v204
	v_and_b32_e32 v198, 31, v249
	v_lshrrev_b32_e32 v199, 5, v249
	v_and_b32_e32 v208, 15, v249
	v_lshrrev_b32_e32 v209, 4, v249
	s_lshl_b32 s40, s40, 14
	v_and_b32_e32 v238, 15, v198
	v_xor_b32_e32 v238, v238, v199
	v_lshl_add_u32 v239, v198, 8, s40
	v_xor_b32_e32 v228, 0, v238
	v_lshl_add_u32 v228, v228, 4, v239
	v_xor_b32_e32 v229, 2, v238
	v_lshl_add_u32 v229, v229, 4, v239
	v_xor_b32_e32 v230, 4, v238
	v_lshl_add_u32 v230, v230, 4, v239
	v_xor_b32_e32 v231, 6, v238
	v_lshl_add_u32 v231, v231, 4, v239
	v_xor_b32_e32 v232, 8, v238
	v_lshl_add_u32 v232, v232, 4, v239
	v_xor_b32_e32 v233, 10, v238
	v_lshl_add_u32 v233, v233, 4, v239
	v_xor_b32_e32 v234, 12, v238
	v_lshl_add_u32 v234, v234, 4, v239
	v_xor_b32_e32 v235, 14, v238
	v_lshl_add_u32 v235, v235, 4, v239
	v_lshl_add_u32 v239, v209, 8, s40
	v_add_u32_e32 v210, 0, v209
	v_xor_b32_e32 v210, v210, v208
	v_lshl_add_u32 v210, v210, 4, v239
	v_add_u32_e32 v211, 4, v209
	v_xor_b32_e32 v211, v211, v208
	v_lshl_add_u32 v211, v211, 4, v239
	v_add_u32_e32 v215, 8, v209
	v_xor_b32_e32 v215, v215, v208
	v_lshl_add_u32 v215, v215, 4, v239
	v_add_u32_e32 v237, 12, v209
	v_xor_b32_e32 v237, v237, v208
	v_lshl_add_u32 v237, v237, 4, v239
	v_lshlrev_b32_e32 v247, 12, v209
	v_lshl_add_u32 v247, v208, 4, v247
	v_lshrrev_b32_e32 v248, 1, v247
	v_lshlrev_b32_e32 v249, 6, v209
	s_mov_b32 s48, 0x00010001
	s_mov_b32 s49, 0x00010001
	global_load_dwordx4 v[130:133], v247, s[36:37]
	s_add_u32 s36, s36, 0x4000
	s_addc_u32 s37, s37, 0
	global_load_dwordx4 v[134:137], v247, s[36:37]
	s_add_u32 s36, s36, 0x4000
	s_addc_u32 s37, s37, 0
	global_load_dwordx4 v[138:141], v247, s[36:37]
	s_add_u32 s36, s36, 0x4000
	s_addc_u32 s37, s37, 0
	global_load_dwordx4 v[142:145], v247, s[36:37]
	s_add_u32 s36, s36, 0x4000
	s_addc_u32 s37, s37, 0
	global_load_dwordx4 v[146:149], v247, s[36:37]
	s_add_u32 s36, s36, 0x4000
	s_addc_u32 s37, s37, 0
	global_load_dwordx4 v[150:153], v247, s[36:37]
	s_add_u32 s36, s36, 0x4000
	s_addc_u32 s37, s37, 0
	global_load_dwordx4 v[154:157], v247, s[36:37]
	s_add_u32 s36, s36, 0x4000
	s_addc_u32 s37, s37, 0
	global_load_dwordx4 v[158:161], v247, s[36:37]
	s_add_u32 s36, s36, 0x4000
	s_addc_u32 s37, s37, 0
	global_load_dwordx4 v[162:165], v247, s[36:37]
	s_add_u32 s36, s36, 0x4000
	s_addc_u32 s37, s37, 0
	global_load_dwordx4 v[166:169], v247, s[36:37]
	s_add_u32 s36, s36, 0x4000
	s_addc_u32 s37, s37, 0
	global_load_dwordx4 v[170:173], v247, s[36:37]
	s_add_u32 s36, s36, 0x4000
	s_addc_u32 s37, s37, 0
	global_load_dwordx4 v[174:177], v247, s[36:37]
	s_add_u32 s36, s36, 0x4000
	s_addc_u32 s37, s37, 0
	global_load_dwordx4 v[200:203], v247, s[36:37]
	s_add_u32 s36, s36, 0x4000
	s_addc_u32 s37, s37, 0
	global_load_dwordx4 v[216:219], v247, s[36:37]
	s_add_u32 s36, s36, 0x4000
	s_addc_u32 s37, s37, 0
	global_load_dwordx4 v[220:223], v247, s[36:37]
	s_add_u32 s36, s36, 0x4000
	s_addc_u32 s37, s37, 0
	global_load_dwordx4 v[224:227], v247, s[36:37]
	s_add_u32 s36, s36, 0x4000
	s_addc_u32 s37, s37, 0
	ds_write_b128 v228, v[82:85]
	ds_write_b128 v229, v[86:89]
	ds_write_b128 v230, v[90:93]
	ds_write_b128 v231, v[94:97]
	ds_write_b128 v232, v[114:117]
	ds_write_b128 v233, v[118:121]
	ds_write_b128 v234, v[122:125]
	ds_write_b128 v235, v[126:129]
	ds_write_b128 v228, v[66:69] offset:8192
	ds_write_b128 v229, v[70:73] offset:8192
	ds_write_b128 v230, v[74:77] offset:8192
	ds_write_b128 v231, v[78:81] offset:8192
	ds_write_b128 v232, v[98:101] offset:8192
	ds_write_b128 v233, v[102:105] offset:8192
	ds_write_b128 v234, v[106:109] offset:8192
	ds_write_b128 v235, v[110:113] offset:8192
	global_load_dwordx4 v[82:85], v247, s[36:37]
	s_add_u32 s36, s36, 0x4000
	s_addc_u32 s37, s37, 0
	global_load_dwordx4 v[86:89], v247, s[36:37]
	s_add_u32 s36, s36, 0x4000
	s_addc_u32 s37, s37, 0
	global_load_dwordx4 v[90:93], v247, s[36:37]
	s_add_u32 s36, s36, 0x4000
	s_addc_u32 s37, s37, 0
	global_load_dwordx4 v[94:97], v247, s[36:37]
	s_add_u32 s36, s36, 0x4000
	s_addc_u32 s37, s37, 0
	global_load_dwordx4 v[114:117], v247, s[36:37]
	s_add_u32 s36, s36, 0x4000
	s_addc_u32 s37, s37, 0
	global_load_dwordx4 v[118:121], v247, s[36:37]
	s_add_u32 s36, s36, 0x4000
	s_addc_u32 s37, s37, 0
	global_load_dwordx4 v[122:125], v247, s[36:37]
	s_add_u32 s36, s36, 0x4000
	s_addc_u32 s37, s37, 0
	global_load_dwordx4 v[126:129], v247, s[36:37]
	s_add_u32 s36, s36, 0x4000
	s_addc_u32 s37, s37, 0
	global_load_dwordx4 v[66:69], v247, s[36:37]
	s_add_u32 s36, s36, 0x4000
	s_addc_u32 s37, s37, 0
	global_load_dwordx4 v[70:73], v247, s[36:37]
	s_add_u32 s36, s36, 0x4000
	s_addc_u32 s37, s37, 0
	global_load_dwordx4 v[74:77], v247, s[36:37]
	s_add_u32 s36, s36, 0x4000
	s_addc_u32 s37, s37, 0
	global_load_dwordx4 v[78:81], v247, s[36:37]
	s_add_u32 s36, s36, 0x4000
	s_addc_u32 s37, s37, 0
	global_load_dwordx4 v[98:101], v247, s[36:37]
	s_add_u32 s36, s36, 0x4000
	s_addc_u32 s37, s37, 0
	global_load_dwordx4 v[102:105], v247, s[36:37]
	s_add_u32 s36, s36, 0x4000
	s_addc_u32 s37, s37, 0
	global_load_dwordx4 v[106:109], v247, s[36:37]
	s_add_u32 s36, s36, 0x4000
	s_addc_u32 s37, s37, 0
	global_load_dwordx4 v[110:113], v247, s[36:37]
	s_add_u32 s36, s36, 0x4000
	s_addc_u32 s37, s37, 0
	s_waitcnt lgkmcnt(0)
	ds_read_b128 v[228:231], v210 offset:0
	ds_read_b128 v[238:241], v211 offset:1024
	s_waitcnt vmcnt(31) lgkmcnt(1)
	v_pk_add_f32 v[130:131], v[228:229], v[130:131]
	v_pk_add_f32 v[132:133], v[230:231], v[132:133]
	v_pk_mul_f32 v[232:233], v[130:131], v[130:131]
	v_pk_mul_f32 v[234:235], v[132:133], v[132:133]
	ds_read_b128 v[228:231], v215 offset:2048
	v_add_f32_e32 v236, v232, v233
	v_add_f32_e32 v236, v234, v236
	v_add_f32_e32 v236, v235, v236
	global_store_dwordx4 v247, v[130:133], s[38:39]
	v_cvt_pk_bf16_f32 v232, v130, v131
	v_cvt_pk_bf16_f32 v233, v132, v133
	v_add_f32_dpp v236, v236, v236 quad_perm:[1,0,3,2] row_mask:0xf bank_mask:0xf
	global_store_dwordx2 v248, v[232:233], s[50:51]
	s_add_u32 s38, s38, 0x4000
	s_addc_u32 s39, s39, 0
	v_add_f32_dpp v236, v236, v236 quad_perm:[2,3,0,1] row_mask:0xf bank_mask:0xf
	s_add_u32 s50, s50, 0x2000
	s_addc_u32 s51, s51, 0
	v_add_f32_dpp v236, v236, v236 row_half_mirror row_mask:0xf bank_mask:0xf
	s_nop 1
	v_add_f32_dpp v236, v236, v236 row_mirror row_mask:0xf bank_mask:0xf
	s_mov_b64 exec, s[48:49]
	global_store_dword v249, v236, s[34:35] offset:0
	s_mov_b64 exec, -1
	s_waitcnt vmcnt(33) lgkmcnt(1)
	v_pk_add_f32 v[134:135], v[238:239], v[134:135]
	v_pk_add_f32 v[136:137], v[240:241], v[136:137]
	v_pk_mul_f32 v[242:243], v[134:135], v[134:135]
	v_pk_mul_f32 v[244:245], v[136:137], v[136:137]
	ds_read_b128 v[238:241], v237 offset:3072
	v_add_f32_e32 v246, v242, v243
	v_add_f32_e32 v246, v244, v246
	v_add_f32_e32 v246, v245, v246
	global_store_dwordx4 v247, v[134:137], s[38:39]
	v_cvt_pk_bf16_f32 v242, v134, v135
	v_cvt_pk_bf16_f32 v243, v136, v137
	v_add_f32_dpp v246, v246, v246 quad_perm:[1,0,3,2] row_mask:0xf bank_mask:0xf
	global_store_dwordx2 v248, v[242:243], s[50:51]
	s_add_u32 s38, s38, 0x4000
	s_addc_u32 s39, s39, 0
	v_add_f32_dpp v246, v246, v246 quad_perm:[2,3,0,1] row_mask:0xf bank_mask:0xf
	s_add_u32 s50, s50, 0x2000
	s_addc_u32 s51, s51, 0
	v_add_f32_dpp v246, v246, v246 row_half_mirror row_mask:0xf bank_mask:0xf
	s_nop 1
	v_add_f32_dpp v246, v246, v246 row_mirror row_mask:0xf bank_mask:0xf
	s_mov_b64 exec, s[48:49]
	global_store_dword v249, v246, s[34:35] offset:256
	s_mov_b64 exec, -1
	s_waitcnt vmcnt(35) lgkmcnt(1)
	v_pk_add_f32 v[138:139], v[228:229], v[138:139]
	v_pk_add_f32 v[140:141], v[230:231], v[140:141]
	v_pk_mul_f32 v[232:233], v[138:139], v[138:139]
	v_pk_mul_f32 v[234:235], v[140:141], v[140:141]
	ds_read_b128 v[228:231], v210 offset:4096
	v_add_f32_e32 v236, v232, v233
	v_add_f32_e32 v236, v234, v236
	v_add_f32_e32 v236, v235, v236
	global_store_dwordx4 v247, v[138:141], s[38:39]
	v_cvt_pk_bf16_f32 v232, v138, v139
	v_cvt_pk_bf16_f32 v233, v140, v141
	v_add_f32_dpp v236, v236, v236 quad_perm:[1,0,3,2] row_mask:0xf bank_mask:0xf
	global_store_dwordx2 v248, v[232:233], s[50:51]
	s_add_u32 s38, s38, 0x4000
	s_addc_u32 s39, s39, 0
	v_add_f32_dpp v236, v236, v236 quad_perm:[2,3,0,1] row_mask:0xf bank_mask:0xf
	s_add_u32 s50, s50, 0x2000
	s_addc_u32 s51, s51, 0
	v_add_f32_dpp v236, v236, v236 row_half_mirror row_mask:0xf bank_mask:0xf
	s_nop 1
	v_add_f32_dpp v236, v236, v236 row_mirror row_mask:0xf bank_mask:0xf
	s_mov_b64 exec, s[48:49]
	global_store_dword v249, v236, s[34:35] offset:512
	s_mov_b64 exec, -1
	s_waitcnt vmcnt(37) lgkmcnt(1)
	v_pk_add_f32 v[142:143], v[238:239], v[142:143]
	v_pk_add_f32 v[144:145], v[240:241], v[144:145]
	v_pk_mul_f32 v[242:243], v[142:143], v[142:143]
	v_pk_mul_f32 v[244:245], v[144:145], v[144:145]
	ds_read_b128 v[238:241], v211 offset:5120
	v_add_f32_e32 v246, v242, v243
	v_add_f32_e32 v246, v244, v246
	v_add_f32_e32 v246, v245, v246
	global_store_dwordx4 v247, v[142:145], s[38:39]
	v_cvt_pk_bf16_f32 v242, v142, v143
	v_cvt_pk_bf16_f32 v243, v144, v145
	v_add_f32_dpp v246, v246, v246 quad_perm:[1,0,3,2] row_mask:0xf bank_mask:0xf
	global_store_dwordx2 v248, v[242:243], s[50:51]
	s_add_u32 s38, s38, 0x4000
	s_addc_u32 s39, s39, 0
	v_add_f32_dpp v246, v246, v246 quad_perm:[2,3,0,1] row_mask:0xf bank_mask:0xf
	s_add_u32 s50, s50, 0x2000
	s_addc_u32 s51, s51, 0
	v_add_f32_dpp v246, v246, v246 row_half_mirror row_mask:0xf bank_mask:0xf
	s_nop 1
	v_add_f32_dpp v246, v246, v246 row_mirror row_mask:0xf bank_mask:0xf
	s_mov_b64 exec, s[48:49]
	global_store_dword v249, v246, s[34:35] offset:768
	s_mov_b64 exec, -1
	s_waitcnt vmcnt(39) lgkmcnt(1)
	v_pk_add_f32 v[146:147], v[228:229], v[146:147]
	v_pk_add_f32 v[148:149], v[230:231], v[148:149]
	v_pk_mul_f32 v[232:233], v[146:147], v[146:147]
	v_pk_mul_f32 v[234:235], v[148:149], v[148:149]
	ds_read_b128 v[228:231], v215 offset:6144
	v_add_f32_e32 v236, v232, v233
	v_add_f32_e32 v236, v234, v236
	v_add_f32_e32 v236, v235, v236
	global_store_dwordx4 v247, v[146:149], s[38:39]
	v_cvt_pk_bf16_f32 v232, v146, v147
	v_cvt_pk_bf16_f32 v233, v148, v149
	v_add_f32_dpp v236, v236, v236 quad_perm:[1,0,3,2] row_mask:0xf bank_mask:0xf
	global_store_dwordx2 v248, v[232:233], s[50:51]
	s_add_u32 s38, s38, 0x4000
	s_addc_u32 s39, s39, 0
	v_add_f32_dpp v236, v236, v236 quad_perm:[2,3,0,1] row_mask:0xf bank_mask:0xf
	s_add_u32 s50, s50, 0x2000
	s_addc_u32 s51, s51, 0
	v_add_f32_dpp v236, v236, v236 row_half_mirror row_mask:0xf bank_mask:0xf
	s_nop 1
	v_add_f32_dpp v236, v236, v236 row_mirror row_mask:0xf bank_mask:0xf
	s_mov_b64 exec, s[48:49]
	global_store_dword v249, v236, s[34:35] offset:1024
	s_mov_b64 exec, -1
	s_waitcnt vmcnt(41) lgkmcnt(1)
	v_pk_add_f32 v[150:151], v[238:239], v[150:151]
	v_pk_add_f32 v[152:153], v[240:241], v[152:153]
	v_pk_mul_f32 v[242:243], v[150:151], v[150:151]
	v_pk_mul_f32 v[244:245], v[152:153], v[152:153]
	ds_read_b128 v[238:241], v237 offset:7168
	v_add_f32_e32 v246, v242, v243
	v_add_f32_e32 v246, v244, v246
	v_add_f32_e32 v246, v245, v246
	global_store_dwordx4 v247, v[150:153], s[38:39]
	v_cvt_pk_bf16_f32 v242, v150, v151
	v_cvt_pk_bf16_f32 v243, v152, v153
	v_add_f32_dpp v246, v246, v246 quad_perm:[1,0,3,2] row_mask:0xf bank_mask:0xf
	global_store_dwordx2 v248, v[242:243], s[50:51]
	s_add_u32 s38, s38, 0x4000
	s_addc_u32 s39, s39, 0
	v_add_f32_dpp v246, v246, v246 quad_perm:[2,3,0,1] row_mask:0xf bank_mask:0xf
	s_add_u32 s50, s50, 0x2000
	s_addc_u32 s51, s51, 0
	v_add_f32_dpp v246, v246, v246 row_half_mirror row_mask:0xf bank_mask:0xf
	s_nop 1
	v_add_f32_dpp v246, v246, v246 row_mirror row_mask:0xf bank_mask:0xf
	s_mov_b64 exec, s[48:49]
	global_store_dword v249, v246, s[34:35] offset:1280
	s_mov_b64 exec, -1
	s_waitcnt vmcnt(43) lgkmcnt(1)
	v_pk_add_f32 v[154:155], v[228:229], v[154:155]
	v_pk_add_f32 v[156:157], v[230:231], v[156:157]
	v_pk_mul_f32 v[232:233], v[154:155], v[154:155]
	v_pk_mul_f32 v[234:235], v[156:157], v[156:157]
	ds_read_b128 v[228:231], v210 offset:8192
	v_add_f32_e32 v236, v232, v233
	v_add_f32_e32 v236, v234, v236
	v_add_f32_e32 v236, v235, v236
	global_store_dwordx4 v247, v[154:157], s[38:39]
	v_cvt_pk_bf16_f32 v232, v154, v155
	v_cvt_pk_bf16_f32 v233, v156, v157
	v_add_f32_dpp v236, v236, v236 quad_perm:[1,0,3,2] row_mask:0xf bank_mask:0xf
	global_store_dwordx2 v248, v[232:233], s[50:51]
	s_add_u32 s38, s38, 0x4000
	s_addc_u32 s39, s39, 0
	v_add_f32_dpp v236, v236, v236 quad_perm:[2,3,0,1] row_mask:0xf bank_mask:0xf
	s_add_u32 s50, s50, 0x2000
	s_addc_u32 s51, s51, 0
	v_add_f32_dpp v236, v236, v236 row_half_mirror row_mask:0xf bank_mask:0xf
	s_nop 1
	v_add_f32_dpp v236, v236, v236 row_mirror row_mask:0xf bank_mask:0xf
	s_mov_b64 exec, s[48:49]
	global_store_dword v249, v236, s[34:35] offset:1536
	s_mov_b64 exec, -1
	s_waitcnt vmcnt(45) lgkmcnt(1)
	v_pk_add_f32 v[158:159], v[238:239], v[158:159]
	v_pk_add_f32 v[160:161], v[240:241], v[160:161]
	v_pk_mul_f32 v[242:243], v[158:159], v[158:159]
	v_pk_mul_f32 v[244:245], v[160:161], v[160:161]
	ds_read_b128 v[238:241], v211 offset:9216
	v_add_f32_e32 v246, v242, v243
	v_add_f32_e32 v246, v244, v246
	v_add_f32_e32 v246, v245, v246
	global_store_dwordx4 v247, v[158:161], s[38:39]
	v_cvt_pk_bf16_f32 v242, v158, v159
	v_cvt_pk_bf16_f32 v243, v160, v161
	v_add_f32_dpp v246, v246, v246 quad_perm:[1,0,3,2] row_mask:0xf bank_mask:0xf
	global_store_dwordx2 v248, v[242:243], s[50:51]
	s_add_u32 s38, s38, 0x4000
	s_addc_u32 s39, s39, 0
	v_add_f32_dpp v246, v246, v246 quad_perm:[2,3,0,1] row_mask:0xf bank_mask:0xf
	s_add_u32 s50, s50, 0x2000
	s_addc_u32 s51, s51, 0
	v_add_f32_dpp v246, v246, v246 row_half_mirror row_mask:0xf bank_mask:0xf
	s_nop 1
	v_add_f32_dpp v246, v246, v246 row_mirror row_mask:0xf bank_mask:0xf
	s_mov_b64 exec, s[48:49]
	global_store_dword v249, v246, s[34:35] offset:1792
	s_mov_b64 exec, -1
	s_waitcnt vmcnt(47) lgkmcnt(1)
	v_pk_add_f32 v[162:163], v[228:229], v[162:163]
	v_pk_add_f32 v[164:165], v[230:231], v[164:165]
	v_pk_mul_f32 v[232:233], v[162:163], v[162:163]
	v_pk_mul_f32 v[234:235], v[164:165], v[164:165]
	ds_read_b128 v[228:231], v215 offset:10240
	v_add_f32_e32 v236, v232, v233
	v_add_f32_e32 v236, v234, v236
	v_add_f32_e32 v236, v235, v236
	global_store_dwordx4 v247, v[162:165], s[38:39]
	v_cvt_pk_bf16_f32 v232, v162, v163
	v_cvt_pk_bf16_f32 v233, v164, v165
	v_add_f32_dpp v236, v236, v236 quad_perm:[1,0,3,2] row_mask:0xf bank_mask:0xf
	global_store_dwordx2 v248, v[232:233], s[50:51]
	s_add_u32 s38, s38, 0x4000
	s_addc_u32 s39, s39, 0
	v_add_f32_dpp v236, v236, v236 quad_perm:[2,3,0,1] row_mask:0xf bank_mask:0xf
	s_add_u32 s50, s50, 0x2000
	s_addc_u32 s51, s51, 0
	v_add_f32_dpp v236, v236, v236 row_half_mirror row_mask:0xf bank_mask:0xf
	s_nop 1
	v_add_f32_dpp v236, v236, v236 row_mirror row_mask:0xf bank_mask:0xf
	s_mov_b64 exec, s[48:49]
	global_store_dword v249, v236, s[34:35] offset:2048
	s_mov_b64 exec, -1
	s_waitcnt vmcnt(49) lgkmcnt(1)
	v_pk_add_f32 v[166:167], v[238:239], v[166:167]
	v_pk_add_f32 v[168:169], v[240:241], v[168:169]
	v_pk_mul_f32 v[242:243], v[166:167], v[166:167]
	v_pk_mul_f32 v[244:245], v[168:169], v[168:169]
	ds_read_b128 v[238:241], v237 offset:11264
	v_add_f32_e32 v246, v242, v243
	v_add_f32_e32 v246, v244, v246
	v_add_f32_e32 v246, v245, v246
	global_store_dwordx4 v247, v[166:169], s[38:39]
	v_cvt_pk_bf16_f32 v242, v166, v167
	v_cvt_pk_bf16_f32 v243, v168, v169
	v_add_f32_dpp v246, v246, v246 quad_perm:[1,0,3,2] row_mask:0xf bank_mask:0xf
	global_store_dwordx2 v248, v[242:243], s[50:51]
	s_add_u32 s38, s38, 0x4000
	s_addc_u32 s39, s39, 0
	v_add_f32_dpp v246, v246, v246 quad_perm:[2,3,0,1] row_mask:0xf bank_mask:0xf
	s_add_u32 s50, s50, 0x2000
	s_addc_u32 s51, s51, 0
	v_add_f32_dpp v246, v246, v246 row_half_mirror row_mask:0xf bank_mask:0xf
	s_nop 1
	v_add_f32_dpp v246, v246, v246 row_mirror row_mask:0xf bank_mask:0xf
	s_mov_b64 exec, s[48:49]
	global_store_dword v249, v246, s[34:35] offset:2304
	s_mov_b64 exec, -1
	s_waitcnt vmcnt(51) lgkmcnt(1)
	v_pk_add_f32 v[170:171], v[228:229], v[170:171]
	v_pk_add_f32 v[172:173], v[230:231], v[172:173]
	v_pk_mul_f32 v[232:233], v[170:171], v[170:171]
	v_pk_mul_f32 v[234:235], v[172:173], v[172:173]
	ds_read_b128 v[228:231], v210 offset:12288
	v_add_f32_e32 v236, v232, v233
	v_add_f32_e32 v236, v234, v236
	v_add_f32_e32 v236, v235, v236
	global_store_dwordx4 v247, v[170:173], s[38:39]
	v_cvt_pk_bf16_f32 v232, v170, v171
	v_cvt_pk_bf16_f32 v233, v172, v173
	v_add_f32_dpp v236, v236, v236 quad_perm:[1,0,3,2] row_mask:0xf bank_mask:0xf
	global_store_dwordx2 v248, v[232:233], s[50:51]
	s_add_u32 s38, s38, 0x4000
	s_addc_u32 s39, s39, 0
	v_add_f32_dpp v236, v236, v236 quad_perm:[2,3,0,1] row_mask:0xf bank_mask:0xf
	s_add_u32 s50, s50, 0x2000
	s_addc_u32 s51, s51, 0
	v_add_f32_dpp v236, v236, v236 row_half_mirror row_mask:0xf bank_mask:0xf
	s_nop 1
	v_add_f32_dpp v236, v236, v236 row_mirror row_mask:0xf bank_mask:0xf
	s_mov_b64 exec, s[48:49]
	global_store_dword v249, v236, s[34:35] offset:2560
	s_mov_b64 exec, -1
	s_waitcnt vmcnt(53) lgkmcnt(1)
	v_pk_add_f32 v[174:175], v[238:239], v[174:175]
	v_pk_add_f32 v[176:177], v[240:241], v[176:177]
	v_pk_mul_f32 v[242:243], v[174:175], v[174:175]
	v_pk_mul_f32 v[244:245], v[176:177], v[176:177]
	ds_read_b128 v[238:241], v211 offset:13312
	v_add_f32_e32 v246, v242, v243
	v_add_f32_e32 v246, v244, v246
	v_add_f32_e32 v246, v245, v246
	global_store_dwordx4 v247, v[174:177], s[38:39]
	v_cvt_pk_bf16_f32 v242, v174, v175
	v_cvt_pk_bf16_f32 v243, v176, v177
	v_add_f32_dpp v246, v246, v246 quad_perm:[1,0,3,2] row_mask:0xf bank_mask:0xf
	global_store_dwordx2 v248, v[242:243], s[50:51]
	s_add_u32 s38, s38, 0x4000
	s_addc_u32 s39, s39, 0
	v_add_f32_dpp v246, v246, v246 quad_perm:[2,3,0,1] row_mask:0xf bank_mask:0xf
	s_add_u32 s50, s50, 0x2000
	s_addc_u32 s51, s51, 0
	v_add_f32_dpp v246, v246, v246 row_half_mirror row_mask:0xf bank_mask:0xf
	s_nop 1
	v_add_f32_dpp v246, v246, v246 row_mirror row_mask:0xf bank_mask:0xf
	s_mov_b64 exec, s[48:49]
	global_store_dword v249, v246, s[34:35] offset:2816
	s_mov_b64 exec, -1
	s_waitcnt vmcnt(55) lgkmcnt(1)
	v_pk_add_f32 v[200:201], v[228:229], v[200:201]
	v_pk_add_f32 v[202:203], v[230:231], v[202:203]
	v_pk_mul_f32 v[232:233], v[200:201], v[200:201]
	v_pk_mul_f32 v[234:235], v[202:203], v[202:203]
	ds_read_b128 v[228:231], v215 offset:14336
	v_add_f32_e32 v236, v232, v233
	v_add_f32_e32 v236, v234, v236
	v_add_f32_e32 v236, v235, v236
	global_store_dwordx4 v247, v[200:203], s[38:39]
	v_cvt_pk_bf16_f32 v232, v200, v201
	v_cvt_pk_bf16_f32 v233, v202, v203
	v_add_f32_dpp v236, v236, v236 quad_perm:[1,0,3,2] row_mask:0xf bank_mask:0xf
	global_store_dwordx2 v248, v[232:233], s[50:51]
	s_add_u32 s38, s38, 0x4000
	s_addc_u32 s39, s39, 0
	v_add_f32_dpp v236, v236, v236 quad_perm:[2,3,0,1] row_mask:0xf bank_mask:0xf
	s_add_u32 s50, s50, 0x2000
	s_addc_u32 s51, s51, 0
	v_add_f32_dpp v236, v236, v236 row_half_mirror row_mask:0xf bank_mask:0xf
	s_nop 1
	v_add_f32_dpp v236, v236, v236 row_mirror row_mask:0xf bank_mask:0xf
	s_mov_b64 exec, s[48:49]
	global_store_dword v249, v236, s[34:35] offset:3072
	s_mov_b64 exec, -1
	s_waitcnt vmcnt(57) lgkmcnt(1)
	v_pk_add_f32 v[216:217], v[238:239], v[216:217]
	v_pk_add_f32 v[218:219], v[240:241], v[218:219]
	v_pk_mul_f32 v[242:243], v[216:217], v[216:217]
	v_pk_mul_f32 v[244:245], v[218:219], v[218:219]
	ds_read_b128 v[238:241], v237 offset:15360
	v_add_f32_e32 v246, v242, v243
	v_add_f32_e32 v246, v244, v246
	v_add_f32_e32 v246, v245, v246
	global_store_dwordx4 v247, v[216:219], s[38:39]
	v_cvt_pk_bf16_f32 v242, v216, v217
	v_cvt_pk_bf16_f32 v243, v218, v219
	v_add_f32_dpp v246, v246, v246 quad_perm:[1,0,3,2] row_mask:0xf bank_mask:0xf
	global_store_dwordx2 v248, v[242:243], s[50:51]
	s_add_u32 s38, s38, 0x4000
	s_addc_u32 s39, s39, 0
	v_add_f32_dpp v246, v246, v246 quad_perm:[2,3,0,1] row_mask:0xf bank_mask:0xf
	s_add_u32 s50, s50, 0x2000
	s_addc_u32 s51, s51, 0
	v_add_f32_dpp v246, v246, v246 row_half_mirror row_mask:0xf bank_mask:0xf
	s_nop 1
	v_add_f32_dpp v246, v246, v246 row_mirror row_mask:0xf bank_mask:0xf
	s_mov_b64 exec, s[48:49]
	global_store_dword v249, v246, s[34:35] offset:3328
	s_mov_b64 exec, -1
	s_waitcnt vmcnt(59) lgkmcnt(1)
	v_pk_add_f32 v[220:221], v[228:229], v[220:221]
	v_pk_add_f32 v[222:223], v[230:231], v[222:223]
	v_pk_mul_f32 v[232:233], v[220:221], v[220:221]
	v_pk_mul_f32 v[234:235], v[222:223], v[222:223]
	v_add_f32_e32 v236, v232, v233
	v_add_f32_e32 v236, v234, v236
	v_add_f32_e32 v236, v235, v236
	global_store_dwordx4 v247, v[220:223], s[38:39]
	v_cvt_pk_bf16_f32 v232, v220, v221
	v_cvt_pk_bf16_f32 v233, v222, v223
	v_add_f32_dpp v236, v236, v236 quad_perm:[1,0,3,2] row_mask:0xf bank_mask:0xf
	global_store_dwordx2 v248, v[232:233], s[50:51]
	s_add_u32 s38, s38, 0x4000
	s_addc_u32 s39, s39, 0
	v_add_f32_dpp v236, v236, v236 quad_perm:[2,3,0,1] row_mask:0xf bank_mask:0xf
	s_add_u32 s50, s50, 0x2000
	s_addc_u32 s51, s51, 0
	v_add_f32_dpp v236, v236, v236 row_half_mirror row_mask:0xf bank_mask:0xf
	s_nop 1
	v_add_f32_dpp v236, v236, v236 row_mirror row_mask:0xf bank_mask:0xf
	s_mov_b64 exec, s[48:49]
	global_store_dword v249, v236, s[34:35] offset:3584
	s_mov_b64 exec, -1
	s_waitcnt vmcnt(61) lgkmcnt(0)
	v_pk_add_f32 v[224:225], v[238:239], v[224:225]
	v_pk_add_f32 v[226:227], v[240:241], v[226:227]
	v_pk_mul_f32 v[242:243], v[224:225], v[224:225]
	v_pk_mul_f32 v[244:245], v[226:227], v[226:227]
	v_add_f32_e32 v246, v242, v243
	v_add_f32_e32 v246, v244, v246
	v_add_f32_e32 v246, v245, v246
	global_store_dwordx4 v247, v[224:227], s[38:39]
	v_cvt_pk_bf16_f32 v242, v224, v225
	v_cvt_pk_bf16_f32 v243, v226, v227
	v_add_f32_dpp v246, v246, v246 quad_perm:[1,0,3,2] row_mask:0xf bank_mask:0xf
	global_store_dwordx2 v248, v[242:243], s[50:51]
	s_add_u32 s38, s38, 0x4000
	s_addc_u32 s39, s39, 0
	v_add_f32_dpp v246, v246, v246 quad_perm:[2,3,0,1] row_mask:0xf bank_mask:0xf
	s_add_u32 s50, s50, 0x2000
	s_addc_u32 s51, s51, 0
	v_add_f32_dpp v246, v246, v246 row_half_mirror row_mask:0xf bank_mask:0xf
	s_nop 1
	v_add_f32_dpp v246, v246, v246 row_mirror row_mask:0xf bank_mask:0xf
	s_mov_b64 exec, s[48:49]
	global_store_dword v249, v246, s[34:35] offset:3840
	s_mov_b64 exec, -1
	s_add_u32 s34, s34, 0x1000
	s_addc_u32 s35, s35, 0
	v_and_b32_e32 v238, 15, v198
	v_xor_b32_e32 v238, v238, v199
	v_lshl_add_u32 v239, v198, 8, s40
	v_xor_b32_e32 v228, 0, v238
	v_lshl_add_u32 v228, v228, 4, v239
	v_xor_b32_e32 v229, 2, v238
	v_lshl_add_u32 v229, v229, 4, v239
	v_xor_b32_e32 v230, 4, v238
	v_lshl_add_u32 v230, v230, 4, v239
	v_xor_b32_e32 v231, 6, v238
	v_lshl_add_u32 v231, v231, 4, v239
	v_xor_b32_e32 v232, 8, v238
	v_lshl_add_u32 v232, v232, 4, v239
	v_xor_b32_e32 v233, 10, v238
	v_lshl_add_u32 v233, v233, 4, v239
	v_xor_b32_e32 v234, 12, v238
	v_lshl_add_u32 v234, v234, 4, v239
	v_xor_b32_e32 v235, 14, v238
	v_lshl_add_u32 v235, v235, 4, v239
	ds_write_b128 v228, v[18:21]
	ds_write_b128 v229, v[22:25]
	ds_write_b128 v230, v[26:29]
	ds_write_b128 v231, v[30:33]
	ds_write_b128 v232, v[50:53]
	ds_write_b128 v233, v[54:57]
	ds_write_b128 v234, v[58:61]
	ds_write_b128 v235, v[62:65]
	ds_write_b128 v228, v[2:5] offset:8192
	ds_write_b128 v229, v[6:9] offset:8192
	ds_write_b128 v230, v[10:13] offset:8192
	ds_write_b128 v231, v[14:17] offset:8192
	ds_write_b128 v232, v[34:37] offset:8192
	ds_write_b128 v233, v[38:41] offset:8192
	ds_write_b128 v234, v[42:45] offset:8192
	ds_write_b128 v235, v[46:49] offset:8192
	s_waitcnt lgkmcnt(0)
	ds_read_b128 v[228:231], v210 offset:0
	ds_read_b128 v[238:241], v211 offset:1024
	s_waitcnt vmcnt(63) lgkmcnt(1)
	v_pk_add_f32 v[82:83], v[228:229], v[82:83]
	v_pk_add_f32 v[84:85], v[230:231], v[84:85]
	v_pk_mul_f32 v[232:233], v[82:83], v[82:83]
	v_pk_mul_f32 v[234:235], v[84:85], v[84:85]
	ds_read_b128 v[228:231], v215 offset:2048
	v_add_f32_e32 v236, v232, v233
	v_add_f32_e32 v236, v234, v236
	v_add_f32_e32 v236, v235, v236
	global_store_dwordx4 v247, v[82:85], s[38:39]
	v_cvt_pk_bf16_f32 v232, v82, v83
	v_cvt_pk_bf16_f32 v233, v84, v85
	v_add_f32_dpp v236, v236, v236 quad_perm:[1,0,3,2] row_mask:0xf bank_mask:0xf
	global_store_dwordx2 v248, v[232:233], s[50:51]
	s_add_u32 s38, s38, 0x4000
	s_addc_u32 s39, s39, 0
	v_add_f32_dpp v236, v236, v236 quad_perm:[2,3,0,1] row_mask:0xf bank_mask:0xf
	s_add_u32 s50, s50, 0x2000
	s_addc_u32 s51, s51, 0
	v_add_f32_dpp v236, v236, v236 row_half_mirror row_mask:0xf bank_mask:0xf
	s_nop 1
	v_add_f32_dpp v236, v236, v236 row_mirror row_mask:0xf bank_mask:0xf
	s_mov_b64 exec, s[48:49]
	global_store_dword v249, v236, s[34:35] offset:0
	s_mov_b64 exec, -1
	s_waitcnt vmcnt(63) lgkmcnt(1)
	v_pk_add_f32 v[86:87], v[238:239], v[86:87]
	v_pk_add_f32 v[88:89], v[240:241], v[88:89]
	v_pk_mul_f32 v[242:243], v[86:87], v[86:87]
	v_pk_mul_f32 v[244:245], v[88:89], v[88:89]
	ds_read_b128 v[238:241], v237 offset:3072
	v_add_f32_e32 v246, v242, v243
	v_add_f32_e32 v246, v244, v246
	v_add_f32_e32 v246, v245, v246
	global_store_dwordx4 v247, v[86:89], s[38:39]
	v_cvt_pk_bf16_f32 v242, v86, v87
	v_cvt_pk_bf16_f32 v243, v88, v89
	v_add_f32_dpp v246, v246, v246 quad_perm:[1,0,3,2] row_mask:0xf bank_mask:0xf
	global_store_dwordx2 v248, v[242:243], s[50:51]
	s_add_u32 s38, s38, 0x4000
	s_addc_u32 s39, s39, 0
	v_add_f32_dpp v246, v246, v246 quad_perm:[2,3,0,1] row_mask:0xf bank_mask:0xf
	s_add_u32 s50, s50, 0x2000
	s_addc_u32 s51, s51, 0
	v_add_f32_dpp v246, v246, v246 row_half_mirror row_mask:0xf bank_mask:0xf
	s_nop 1
	v_add_f32_dpp v246, v246, v246 row_mirror row_mask:0xf bank_mask:0xf
	s_mov_b64 exec, s[48:49]
	global_store_dword v249, v246, s[34:35] offset:256
	s_mov_b64 exec, -1
	s_waitcnt vmcnt(63) lgkmcnt(1)
	v_pk_add_f32 v[90:91], v[228:229], v[90:91]
	v_pk_add_f32 v[92:93], v[230:231], v[92:93]
	v_pk_mul_f32 v[232:233], v[90:91], v[90:91]
	v_pk_mul_f32 v[234:235], v[92:93], v[92:93]
	ds_read_b128 v[228:231], v210 offset:4096
	v_add_f32_e32 v236, v232, v233
	v_add_f32_e32 v236, v234, v236
	v_add_f32_e32 v236, v235, v236
	global_store_dwordx4 v247, v[90:93], s[38:39]
	v_cvt_pk_bf16_f32 v232, v90, v91
	v_cvt_pk_bf16_f32 v233, v92, v93
	v_add_f32_dpp v236, v236, v236 quad_perm:[1,0,3,2] row_mask:0xf bank_mask:0xf
	global_store_dwordx2 v248, v[232:233], s[50:51]
	s_add_u32 s38, s38, 0x4000
	s_addc_u32 s39, s39, 0
	v_add_f32_dpp v236, v236, v236 quad_perm:[2,3,0,1] row_mask:0xf bank_mask:0xf
	s_add_u32 s50, s50, 0x2000
	s_addc_u32 s51, s51, 0
	v_add_f32_dpp v236, v236, v236 row_half_mirror row_mask:0xf bank_mask:0xf
	s_nop 1
	v_add_f32_dpp v236, v236, v236 row_mirror row_mask:0xf bank_mask:0xf
	s_mov_b64 exec, s[48:49]
	global_store_dword v249, v236, s[34:35] offset:512
	s_mov_b64 exec, -1
	s_waitcnt vmcnt(63) lgkmcnt(1)
	v_pk_add_f32 v[94:95], v[238:239], v[94:95]
	v_pk_add_f32 v[96:97], v[240:241], v[96:97]
	v_pk_mul_f32 v[242:243], v[94:95], v[94:95]
	v_pk_mul_f32 v[244:245], v[96:97], v[96:97]
	ds_read_b128 v[238:241], v211 offset:5120
	v_add_f32_e32 v246, v242, v243
	v_add_f32_e32 v246, v244, v246
	v_add_f32_e32 v246, v245, v246
	global_store_dwordx4 v247, v[94:97], s[38:39]
	v_cvt_pk_bf16_f32 v242, v94, v95
	v_cvt_pk_bf16_f32 v243, v96, v97
	v_add_f32_dpp v246, v246, v246 quad_perm:[1,0,3,2] row_mask:0xf bank_mask:0xf
	global_store_dwordx2 v248, v[242:243], s[50:51]
	s_add_u32 s38, s38, 0x4000
	s_addc_u32 s39, s39, 0
	v_add_f32_dpp v246, v246, v246 quad_perm:[2,3,0,1] row_mask:0xf bank_mask:0xf
	s_add_u32 s50, s50, 0x2000
	s_addc_u32 s51, s51, 0
	v_add_f32_dpp v246, v246, v246 row_half_mirror row_mask:0xf bank_mask:0xf
	s_nop 1
	v_add_f32_dpp v246, v246, v246 row_mirror row_mask:0xf bank_mask:0xf
	s_mov_b64 exec, s[48:49]
	global_store_dword v249, v246, s[34:35] offset:768
	s_mov_b64 exec, -1
	s_waitcnt vmcnt(63) lgkmcnt(1)
	v_pk_add_f32 v[114:115], v[228:229], v[114:115]
	v_pk_add_f32 v[116:117], v[230:231], v[116:117]
	v_pk_mul_f32 v[232:233], v[114:115], v[114:115]
	v_pk_mul_f32 v[234:235], v[116:117], v[116:117]
	ds_read_b128 v[228:231], v215 offset:6144
	v_add_f32_e32 v236, v232, v233
	v_add_f32_e32 v236, v234, v236
	v_add_f32_e32 v236, v235, v236
	global_store_dwordx4 v247, v[114:117], s[38:39]
	v_cvt_pk_bf16_f32 v232, v114, v115
	v_cvt_pk_bf16_f32 v233, v116, v117
	v_add_f32_dpp v236, v236, v236 quad_perm:[1,0,3,2] row_mask:0xf bank_mask:0xf
	global_store_dwordx2 v248, v[232:233], s[50:51]
	s_add_u32 s38, s38, 0x4000
	s_addc_u32 s39, s39, 0
	v_add_f32_dpp v236, v236, v236 quad_perm:[2,3,0,1] row_mask:0xf bank_mask:0xf
	s_add_u32 s50, s50, 0x2000
	s_addc_u32 s51, s51, 0
	v_add_f32_dpp v236, v236, v236 row_half_mirror row_mask:0xf bank_mask:0xf
	s_nop 1
	v_add_f32_dpp v236, v236, v236 row_mirror row_mask:0xf bank_mask:0xf
	s_mov_b64 exec, s[48:49]
	global_store_dword v249, v236, s[34:35] offset:1024
	s_mov_b64 exec, -1
	s_waitcnt vmcnt(63) lgkmcnt(1)
	v_pk_add_f32 v[118:119], v[238:239], v[118:119]
	v_pk_add_f32 v[120:121], v[240:241], v[120:121]
	v_pk_mul_f32 v[242:243], v[118:119], v[118:119]
	v_pk_mul_f32 v[244:245], v[120:121], v[120:121]
	ds_read_b128 v[238:241], v237 offset:7168
	v_add_f32_e32 v246, v242, v243
	v_add_f32_e32 v246, v244, v246
	v_add_f32_e32 v246, v245, v246
	global_store_dwordx4 v247, v[118:121], s[38:39]
	v_cvt_pk_bf16_f32 v242, v118, v119
	v_cvt_pk_bf16_f32 v243, v120, v121
	v_add_f32_dpp v246, v246, v246 quad_perm:[1,0,3,2] row_mask:0xf bank_mask:0xf
	global_store_dwordx2 v248, v[242:243], s[50:51]
	s_add_u32 s38, s38, 0x4000
	s_addc_u32 s39, s39, 0
	v_add_f32_dpp v246, v246, v246 quad_perm:[2,3,0,1] row_mask:0xf bank_mask:0xf
	s_add_u32 s50, s50, 0x2000
	s_addc_u32 s51, s51, 0
	v_add_f32_dpp v246, v246, v246 row_half_mirror row_mask:0xf bank_mask:0xf
	s_nop 1
	v_add_f32_dpp v246, v246, v246 row_mirror row_mask:0xf bank_mask:0xf
	s_mov_b64 exec, s[48:49]
	global_store_dword v249, v246, s[34:35] offset:1280
	s_mov_b64 exec, -1
	s_waitcnt vmcnt(63) lgkmcnt(1)
	v_pk_add_f32 v[122:123], v[228:229], v[122:123]
	v_pk_add_f32 v[124:125], v[230:231], v[124:125]
	v_pk_mul_f32 v[232:233], v[122:123], v[122:123]
	v_pk_mul_f32 v[234:235], v[124:125], v[124:125]
	ds_read_b128 v[228:231], v210 offset:8192
	v_add_f32_e32 v236, v232, v233
	v_add_f32_e32 v236, v234, v236
	v_add_f32_e32 v236, v235, v236
	global_store_dwordx4 v247, v[122:125], s[38:39]
	v_cvt_pk_bf16_f32 v232, v122, v123
	v_cvt_pk_bf16_f32 v233, v124, v125
	v_add_f32_dpp v236, v236, v236 quad_perm:[1,0,3,2] row_mask:0xf bank_mask:0xf
	global_store_dwordx2 v248, v[232:233], s[50:51]
	s_add_u32 s38, s38, 0x4000
	s_addc_u32 s39, s39, 0
	v_add_f32_dpp v236, v236, v236 quad_perm:[2,3,0,1] row_mask:0xf bank_mask:0xf
	s_add_u32 s50, s50, 0x2000
	s_addc_u32 s51, s51, 0
	v_add_f32_dpp v236, v236, v236 row_half_mirror row_mask:0xf bank_mask:0xf
	s_nop 1
	v_add_f32_dpp v236, v236, v236 row_mirror row_mask:0xf bank_mask:0xf
	s_mov_b64 exec, s[48:49]
	global_store_dword v249, v236, s[34:35] offset:1536
	s_mov_b64 exec, -1
	s_waitcnt vmcnt(63) lgkmcnt(1)
	v_pk_add_f32 v[126:127], v[238:239], v[126:127]
	v_pk_add_f32 v[128:129], v[240:241], v[128:129]
	v_pk_mul_f32 v[242:243], v[126:127], v[126:127]
	v_pk_mul_f32 v[244:245], v[128:129], v[128:129]
	ds_read_b128 v[238:241], v211 offset:9216
	v_add_f32_e32 v246, v242, v243
	v_add_f32_e32 v246, v244, v246
	v_add_f32_e32 v246, v245, v246
	global_store_dwordx4 v247, v[126:129], s[38:39]
	v_cvt_pk_bf16_f32 v242, v126, v127
	v_cvt_pk_bf16_f32 v243, v128, v129
	v_add_f32_dpp v246, v246, v246 quad_perm:[1,0,3,2] row_mask:0xf bank_mask:0xf
	global_store_dwordx2 v248, v[242:243], s[50:51]
	s_add_u32 s38, s38, 0x4000
	s_addc_u32 s39, s39, 0
	v_add_f32_dpp v246, v246, v246 quad_perm:[2,3,0,1] row_mask:0xf bank_mask:0xf
	s_add_u32 s50, s50, 0x2000
	s_addc_u32 s51, s51, 0
	v_add_f32_dpp v246, v246, v246 row_half_mirror row_mask:0xf bank_mask:0xf
	s_nop 1
	v_add_f32_dpp v246, v246, v246 row_mirror row_mask:0xf bank_mask:0xf
	s_mov_b64 exec, s[48:49]
	global_store_dword v249, v246, s[34:35] offset:1792
	s_mov_b64 exec, -1
	s_waitcnt vmcnt(63) lgkmcnt(1)
	v_pk_add_f32 v[66:67], v[228:229], v[66:67]
	v_pk_add_f32 v[68:69], v[230:231], v[68:69]
	v_pk_mul_f32 v[232:233], v[66:67], v[66:67]
	v_pk_mul_f32 v[234:235], v[68:69], v[68:69]
	ds_read_b128 v[228:231], v215 offset:10240
	v_add_f32_e32 v236, v232, v233
	v_add_f32_e32 v236, v234, v236
	v_add_f32_e32 v236, v235, v236
	global_store_dwordx4 v247, v[66:69], s[38:39]
	v_cvt_pk_bf16_f32 v232, v66, v67
	v_cvt_pk_bf16_f32 v233, v68, v69
	v_add_f32_dpp v236, v236, v236 quad_perm:[1,0,3,2] row_mask:0xf bank_mask:0xf
	global_store_dwordx2 v248, v[232:233], s[50:51]
	s_add_u32 s38, s38, 0x4000
	s_addc_u32 s39, s39, 0
	v_add_f32_dpp v236, v236, v236 quad_perm:[2,3,0,1] row_mask:0xf bank_mask:0xf
	s_add_u32 s50, s50, 0x2000
	s_addc_u32 s51, s51, 0
	v_add_f32_dpp v236, v236, v236 row_half_mirror row_mask:0xf bank_mask:0xf
	s_nop 1
	v_add_f32_dpp v236, v236, v236 row_mirror row_mask:0xf bank_mask:0xf
	s_mov_b64 exec, s[48:49]
	global_store_dword v249, v236, s[34:35] offset:2048
	s_mov_b64 exec, -1
	s_waitcnt vmcnt(63) lgkmcnt(1)
	v_pk_add_f32 v[70:71], v[238:239], v[70:71]
	v_pk_add_f32 v[72:73], v[240:241], v[72:73]
	v_pk_mul_f32 v[242:243], v[70:71], v[70:71]
	v_pk_mul_f32 v[244:245], v[72:73], v[72:73]
	ds_read_b128 v[238:241], v237 offset:11264
	v_add_f32_e32 v246, v242, v243
	v_add_f32_e32 v246, v244, v246
	v_add_f32_e32 v246, v245, v246
	global_store_dwordx4 v247, v[70:73], s[38:39]
	v_cvt_pk_bf16_f32 v242, v70, v71
	v_cvt_pk_bf16_f32 v243, v72, v73
	v_add_f32_dpp v246, v246, v246 quad_perm:[1,0,3,2] row_mask:0xf bank_mask:0xf
	global_store_dwordx2 v248, v[242:243], s[50:51]
	s_add_u32 s38, s38, 0x4000
	s_addc_u32 s39, s39, 0
	v_add_f32_dpp v246, v246, v246 quad_perm:[2,3,0,1] row_mask:0xf bank_mask:0xf
	s_add_u32 s50, s50, 0x2000
	s_addc_u32 s51, s51, 0
	v_add_f32_dpp v246, v246, v246 row_half_mirror row_mask:0xf bank_mask:0xf
	s_nop 1
	v_add_f32_dpp v246, v246, v246 row_mirror row_mask:0xf bank_mask:0xf
	s_mov_b64 exec, s[48:49]
	global_store_dword v249, v246, s[34:35] offset:2304
	s_mov_b64 exec, -1
	s_waitcnt vmcnt(63) lgkmcnt(1)
	v_pk_add_f32 v[74:75], v[228:229], v[74:75]
	v_pk_add_f32 v[76:77], v[230:231], v[76:77]
	v_pk_mul_f32 v[232:233], v[74:75], v[74:75]
	v_pk_mul_f32 v[234:235], v[76:77], v[76:77]
	ds_read_b128 v[228:231], v210 offset:12288
	v_add_f32_e32 v236, v232, v233
	v_add_f32_e32 v236, v234, v236
	v_add_f32_e32 v236, v235, v236
	global_store_dwordx4 v247, v[74:77], s[38:39]
	v_cvt_pk_bf16_f32 v232, v74, v75
	v_cvt_pk_bf16_f32 v233, v76, v77
	v_add_f32_dpp v236, v236, v236 quad_perm:[1,0,3,2] row_mask:0xf bank_mask:0xf
	global_store_dwordx2 v248, v[232:233], s[50:51]
	s_add_u32 s38, s38, 0x4000
	s_addc_u32 s39, s39, 0
	v_add_f32_dpp v236, v236, v236 quad_perm:[2,3,0,1] row_mask:0xf bank_mask:0xf
	s_add_u32 s50, s50, 0x2000
	s_addc_u32 s51, s51, 0
	v_add_f32_dpp v236, v236, v236 row_half_mirror row_mask:0xf bank_mask:0xf
	s_nop 1
	v_add_f32_dpp v236, v236, v236 row_mirror row_mask:0xf bank_mask:0xf
	s_mov_b64 exec, s[48:49]
	global_store_dword v249, v236, s[34:35] offset:2560
	s_mov_b64 exec, -1
	s_waitcnt vmcnt(63) lgkmcnt(1)
	v_pk_add_f32 v[78:79], v[238:239], v[78:79]
	v_pk_add_f32 v[80:81], v[240:241], v[80:81]
	v_pk_mul_f32 v[242:243], v[78:79], v[78:79]
	v_pk_mul_f32 v[244:245], v[80:81], v[80:81]
	ds_read_b128 v[238:241], v211 offset:13312
	v_add_f32_e32 v246, v242, v243
	v_add_f32_e32 v246, v244, v246
	v_add_f32_e32 v246, v245, v246
	global_store_dwordx4 v247, v[78:81], s[38:39]
	v_cvt_pk_bf16_f32 v242, v78, v79
	v_cvt_pk_bf16_f32 v243, v80, v81
	v_add_f32_dpp v246, v246, v246 quad_perm:[1,0,3,2] row_mask:0xf bank_mask:0xf
	global_store_dwordx2 v248, v[242:243], s[50:51]
	s_add_u32 s38, s38, 0x4000
	s_addc_u32 s39, s39, 0
	v_add_f32_dpp v246, v246, v246 quad_perm:[2,3,0,1] row_mask:0xf bank_mask:0xf
	s_add_u32 s50, s50, 0x2000
	s_addc_u32 s51, s51, 0
	v_add_f32_dpp v246, v246, v246 row_half_mirror row_mask:0xf bank_mask:0xf
	s_nop 1
	v_add_f32_dpp v246, v246, v246 row_mirror row_mask:0xf bank_mask:0xf
	s_mov_b64 exec, s[48:49]
	global_store_dword v249, v246, s[34:35] offset:2816
	s_mov_b64 exec, -1
	s_waitcnt vmcnt(63) lgkmcnt(1)
	v_pk_add_f32 v[98:99], v[228:229], v[98:99]
	v_pk_add_f32 v[100:101], v[230:231], v[100:101]
	v_pk_mul_f32 v[232:233], v[98:99], v[98:99]
	v_pk_mul_f32 v[234:235], v[100:101], v[100:101]
	ds_read_b128 v[228:231], v215 offset:14336
	v_add_f32_e32 v236, v232, v233
	v_add_f32_e32 v236, v234, v236
	v_add_f32_e32 v236, v235, v236
	global_store_dwordx4 v247, v[98:101], s[38:39]
	v_cvt_pk_bf16_f32 v232, v98, v99
	v_cvt_pk_bf16_f32 v233, v100, v101
	v_add_f32_dpp v236, v236, v236 quad_perm:[1,0,3,2] row_mask:0xf bank_mask:0xf
	global_store_dwordx2 v248, v[232:233], s[50:51]
	s_add_u32 s38, s38, 0x4000
	s_addc_u32 s39, s39, 0
	v_add_f32_dpp v236, v236, v236 quad_perm:[2,3,0,1] row_mask:0xf bank_mask:0xf
	s_add_u32 s50, s50, 0x2000
	s_addc_u32 s51, s51, 0
	v_add_f32_dpp v236, v236, v236 row_half_mirror row_mask:0xf bank_mask:0xf
	s_nop 1
	v_add_f32_dpp v236, v236, v236 row_mirror row_mask:0xf bank_mask:0xf
	s_mov_b64 exec, s[48:49]
	global_store_dword v249, v236, s[34:35] offset:3072
	s_mov_b64 exec, -1
	s_waitcnt vmcnt(63) lgkmcnt(1)
	v_pk_add_f32 v[102:103], v[238:239], v[102:103]
	v_pk_add_f32 v[104:105], v[240:241], v[104:105]
	v_pk_mul_f32 v[242:243], v[102:103], v[102:103]
	v_pk_mul_f32 v[244:245], v[104:105], v[104:105]
	ds_read_b128 v[238:241], v237 offset:15360
	v_add_f32_e32 v246, v242, v243
	v_add_f32_e32 v246, v244, v246
	v_add_f32_e32 v246, v245, v246
	global_store_dwordx4 v247, v[102:105], s[38:39]
	v_cvt_pk_bf16_f32 v242, v102, v103
	v_cvt_pk_bf16_f32 v243, v104, v105
	v_add_f32_dpp v246, v246, v246 quad_perm:[1,0,3,2] row_mask:0xf bank_mask:0xf
	global_store_dwordx2 v248, v[242:243], s[50:51]
	s_add_u32 s38, s38, 0x4000
	s_addc_u32 s39, s39, 0
	v_add_f32_dpp v246, v246, v246 quad_perm:[2,3,0,1] row_mask:0xf bank_mask:0xf
	s_add_u32 s50, s50, 0x2000
	s_addc_u32 s51, s51, 0
	v_add_f32_dpp v246, v246, v246 row_half_mirror row_mask:0xf bank_mask:0xf
	s_nop 1
	v_add_f32_dpp v246, v246, v246 row_mirror row_mask:0xf bank_mask:0xf
	s_mov_b64 exec, s[48:49]
	global_store_dword v249, v246, s[34:35] offset:3328
	s_mov_b64 exec, -1
	s_waitcnt vmcnt(63) lgkmcnt(1)
	v_pk_add_f32 v[106:107], v[228:229], v[106:107]
	v_pk_add_f32 v[108:109], v[230:231], v[108:109]
	v_pk_mul_f32 v[232:233], v[106:107], v[106:107]
	v_pk_mul_f32 v[234:235], v[108:109], v[108:109]
	v_add_f32_e32 v236, v232, v233
	v_add_f32_e32 v236, v234, v236
	v_add_f32_e32 v236, v235, v236
	global_store_dwordx4 v247, v[106:109], s[38:39]
	v_cvt_pk_bf16_f32 v232, v106, v107
	v_cvt_pk_bf16_f32 v233, v108, v109
	v_add_f32_dpp v236, v236, v236 quad_perm:[1,0,3,2] row_mask:0xf bank_mask:0xf
	global_store_dwordx2 v248, v[232:233], s[50:51]
	s_add_u32 s38, s38, 0x4000
	s_addc_u32 s39, s39, 0
	v_add_f32_dpp v236, v236, v236 quad_perm:[2,3,0,1] row_mask:0xf bank_mask:0xf
	s_add_u32 s50, s50, 0x2000
	s_addc_u32 s51, s51, 0
	v_add_f32_dpp v236, v236, v236 row_half_mirror row_mask:0xf bank_mask:0xf
	s_nop 1
	v_add_f32_dpp v236, v236, v236 row_mirror row_mask:0xf bank_mask:0xf
	s_mov_b64 exec, s[48:49]
	global_store_dword v249, v236, s[34:35] offset:3584
	s_mov_b64 exec, -1
	s_waitcnt vmcnt(63) lgkmcnt(0)
	v_pk_add_f32 v[110:111], v[238:239], v[110:111]
	v_pk_add_f32 v[112:113], v[240:241], v[112:113]
	v_pk_mul_f32 v[242:243], v[110:111], v[110:111]
	v_pk_mul_f32 v[244:245], v[112:113], v[112:113]
	v_add_f32_e32 v246, v242, v243
	v_add_f32_e32 v246, v244, v246
	v_add_f32_e32 v246, v245, v246
	global_store_dwordx4 v247, v[110:113], s[38:39]
	v_cvt_pk_bf16_f32 v242, v110, v111
	v_cvt_pk_bf16_f32 v243, v112, v113
	v_add_f32_dpp v246, v246, v246 quad_perm:[1,0,3,2] row_mask:0xf bank_mask:0xf
	global_store_dwordx2 v248, v[242:243], s[50:51]
	s_add_u32 s38, s38, 0x4000
	s_addc_u32 s39, s39, 0
	v_add_f32_dpp v246, v246, v246 quad_perm:[2,3,0,1] row_mask:0xf bank_mask:0xf
	s_add_u32 s50, s50, 0x2000
	s_addc_u32 s51, s51, 0
	v_add_f32_dpp v246, v246, v246 row_half_mirror row_mask:0xf bank_mask:0xf
	s_nop 1
	v_add_f32_dpp v246, v246, v246 row_mirror row_mask:0xf bank_mask:0xf
	s_mov_b64 exec, s[48:49]
	global_store_dword v249, v246, s[34:35] offset:3840
	s_mov_b64 exec, -1
	s_waitcnt lgkmcnt(0)
	s_branch .LBB0_1122

.LBB0_1526:
	v_readfirstlane_b32 s40, v204
	s_lshr_b32 s40, s40, 6
	s_and_b32 s41, s40, 1
	s_bfe_u32 s42, s40, 0x10001
	s_lshr_b32 s43, s40, 2
	s_lshl_b32 s44, s4, 1
	s_add_i32 s44, s44, s42
	s_lshl_b32 s45, s44, 7
	s_lshl_b32 s46, s41, 6
	s_add_i32 s45, s45, s46
	s_lshl_b32 s46, s43, 7
	s_add_i32 s46, s46, s2
	s_lshl_b32 s47, s44, 1
	s_add_i32 s47, s47, s41
	v_readlane_b32 s36, v251, 50
	v_readlane_b32 s37, v251, 51
	v_readlane_b32 s38, v250, 9
	v_readlane_b32 s39, v250, 10
	v_readlane_b32 s50, v250, 11
	v_readlane_b32 s51, v250, 12
	s_add_u32 s34, s50, 0xf900000
	s_addc_u32 s35, s51, 0
	s_add_u32 s50, s50, 0x5800000
	s_addc_u32 s51, s51, 0
	s_lshl_b32 s48, s46, 12
	s_lshl_b32 s49, s45, 2
	s_add_u32 s48, s48, s49
	s_add_u32 s36, s36, s48
	s_addc_u32 s37, s37, 0
	s_add_u32 s38, s38, s48
	s_addc_u32 s39, s39, 0
	s_lshr_b32 s48, s48, 1
	s_add_u32 s50, s50, s48
	s_addc_u32 s51, s51, 0
	s_lshl_b32 s48, s46, 6
	s_lshl_b32 s49, s47, 2
	s_add_u32 s48, s48, s49
	s_add_u32 s34, s34, s48
	s_addc_u32 s35, s35, 0
	v_and_b32_e32 v249, 63, v204
	v_and_b32_e32 v198, 31, v249
	v_lshrrev_b32_e32 v199, 5, v249
	v_and_b32_e32 v208, 15, v249
	v_lshrrev_b32_e32 v209, 4, v249
	s_lshl_b32 s40, s40, 14
	v_and_b32_e32 v238, 15, v198
	v_xor_b32_e32 v238, v238, v199
	v_lshl_add_u32 v239, v198, 8, s40
	v_xor_b32_e32 v228, 0, v238
	v_lshl_add_u32 v228, v228, 4, v239
	v_xor_b32_e32 v229, 2, v238
	v_lshl_add_u32 v229, v229, 4, v239
	v_xor_b32_e32 v230, 4, v238
	v_lshl_add_u32 v230, v230, 4, v239
	v_xor_b32_e32 v231, 6, v238
	v_lshl_add_u32 v231, v231, 4, v239
	v_xor_b32_e32 v232, 8, v238
	v_lshl_add_u32 v232, v232, 4, v239
	v_xor_b32_e32 v233, 10, v238
	v_lshl_add_u32 v233, v233, 4, v239
	v_xor_b32_e32 v234, 12, v238
	v_lshl_add_u32 v234, v234, 4, v239
	v_xor_b32_e32 v235, 14, v238
	v_lshl_add_u32 v235, v235, 4, v239
	v_lshl_add_u32 v239, v209, 8, s40
	v_add_u32_e32 v210, 0, v209
	v_xor_b32_e32 v210, v210, v208
	v_lshl_add_u32 v210, v210, 4, v239
	v_add_u32_e32 v211, 4, v209
	v_xor_b32_e32 v211, v211, v208
	v_lshl_add_u32 v211, v211, 4, v239
	v_add_u32_e32 v215, 8, v209
	v_xor_b32_e32 v215, v215, v208
	v_lshl_add_u32 v215, v215, 4, v239
	v_add_u32_e32 v237, 12, v209
	v_xor_b32_e32 v237, v237, v208
	v_lshl_add_u32 v237, v237, 4, v239
	v_lshlrev_b32_e32 v247, 12, v209
	v_lshl_add_u32 v247, v208, 4, v247
	v_lshrrev_b32_e32 v248, 1, v247
	v_lshlrev_b32_e32 v249, 6, v209
	s_mov_b32 s48, 0x00010001
	s_mov_b32 s49, 0x00010001
	global_load_dwordx4 v[130:133], v247, s[36:37]
	s_add_u32 s36, s36, 0x4000
	s_addc_u32 s37, s37, 0
	global_load_dwordx4 v[134:137], v247, s[36:37]
	s_add_u32 s36, s36, 0x4000
	s_addc_u32 s37, s37, 0
	global_load_dwordx4 v[138:141], v247, s[36:37]
	s_add_u32 s36, s36, 0x4000
	s_addc_u32 s37, s37, 0
	global_load_dwordx4 v[142:145], v247, s[36:37]
	s_add_u32 s36, s36, 0x4000
	s_addc_u32 s37, s37, 0
	global_load_dwordx4 v[146:149], v247, s[36:37]
	s_add_u32 s36, s36, 0x4000
	s_addc_u32 s37, s37, 0
	global_load_dwordx4 v[150:153], v247, s[36:37]
	s_add_u32 s36, s36, 0x4000
	s_addc_u32 s37, s37, 0
	global_load_dwordx4 v[154:157], v247, s[36:37]
	s_add_u32 s36, s36, 0x4000
	s_addc_u32 s37, s37, 0
	global_load_dwordx4 v[158:161], v247, s[36:37]
	s_add_u32 s36, s36, 0x4000
	s_addc_u32 s37, s37, 0
	global_load_dwordx4 v[162:165], v247, s[36:37]
	s_add_u32 s36, s36, 0x4000
	s_addc_u32 s37, s37, 0
	global_load_dwordx4 v[166:169], v247, s[36:37]
	s_add_u32 s36, s36, 0x4000
	s_addc_u32 s37, s37, 0
	global_load_dwordx4 v[170:173], v247, s[36:37]
	s_add_u32 s36, s36, 0x4000
	s_addc_u32 s37, s37, 0
	global_load_dwordx4 v[188:191], v247, s[36:37]
	s_add_u32 s36, s36, 0x4000
	s_addc_u32 s37, s37, 0
	global_load_dwordx4 v[200:203], v247, s[36:37]
	s_add_u32 s36, s36, 0x4000
	s_addc_u32 s37, s37, 0
	global_load_dwordx4 v[216:219], v247, s[36:37]
	s_add_u32 s36, s36, 0x4000
	s_addc_u32 s37, s37, 0
	global_load_dwordx4 v[220:223], v247, s[36:37]
	s_add_u32 s36, s36, 0x4000
	s_addc_u32 s37, s37, 0
	global_load_dwordx4 v[224:227], v247, s[36:37]
	s_add_u32 s36, s36, 0x4000
	s_addc_u32 s37, s37, 0
	ds_write_b128 v228, v[82:85]
	ds_write_b128 v229, v[86:89]
	ds_write_b128 v230, v[90:93]
	ds_write_b128 v231, v[94:97]
	ds_write_b128 v232, v[114:117]
	ds_write_b128 v233, v[118:121]
	ds_write_b128 v234, v[122:125]
	ds_write_b128 v235, v[126:129]
	ds_write_b128 v228, v[66:69] offset:8192
	ds_write_b128 v229, v[70:73] offset:8192
	ds_write_b128 v230, v[74:77] offset:8192
	ds_write_b128 v231, v[78:81] offset:8192
	ds_write_b128 v232, v[98:101] offset:8192
	ds_write_b128 v233, v[102:105] offset:8192
	ds_write_b128 v234, v[106:109] offset:8192
	ds_write_b128 v235, v[110:113] offset:8192
	global_load_dwordx4 v[82:85], v247, s[36:37]
	s_add_u32 s36, s36, 0x4000
	s_addc_u32 s37, s37, 0
	global_load_dwordx4 v[86:89], v247, s[36:37]
	s_add_u32 s36, s36, 0x4000
	s_addc_u32 s37, s37, 0
	global_load_dwordx4 v[90:93], v247, s[36:37]
	s_add_u32 s36, s36, 0x4000
	s_addc_u32 s37, s37, 0
	global_load_dwordx4 v[94:97], v247, s[36:37]
	s_add_u32 s36, s36, 0x4000
	s_addc_u32 s37, s37, 0
	global_load_dwordx4 v[114:117], v247, s[36:37]
	s_add_u32 s36, s36, 0x4000
	s_addc_u32 s37, s37, 0
	global_load_dwordx4 v[118:121], v247, s[36:37]
	s_add_u32 s36, s36, 0x4000
	s_addc_u32 s37, s37, 0
	global_load_dwordx4 v[122:125], v247, s[36:37]
	s_add_u32 s36, s36, 0x4000
	s_addc_u32 s37, s37, 0
	global_load_dwordx4 v[126:129], v247, s[36:37]
	s_add_u32 s36, s36, 0x4000
	s_addc_u32 s37, s37, 0
	global_load_dwordx4 v[66:69], v247, s[36:37]
	s_add_u32 s36, s36, 0x4000
	s_addc_u32 s37, s37, 0
	global_load_dwordx4 v[70:73], v247, s[36:37]
	s_add_u32 s36, s36, 0x4000
	s_addc_u32 s37, s37, 0
	global_load_dwordx4 v[74:77], v247, s[36:37]
	s_add_u32 s36, s36, 0x4000
	s_addc_u32 s37, s37, 0
	global_load_dwordx4 v[78:81], v247, s[36:37]
	s_add_u32 s36, s36, 0x4000
	s_addc_u32 s37, s37, 0
	global_load_dwordx4 v[98:101], v247, s[36:37]
	s_add_u32 s36, s36, 0x4000
	s_addc_u32 s37, s37, 0
	global_load_dwordx4 v[102:105], v247, s[36:37]
	s_add_u32 s36, s36, 0x4000
	s_addc_u32 s37, s37, 0
	global_load_dwordx4 v[106:109], v247, s[36:37]
	s_add_u32 s36, s36, 0x4000
	s_addc_u32 s37, s37, 0
	global_load_dwordx4 v[110:113], v247, s[36:37]
	s_add_u32 s36, s36, 0x4000
	s_addc_u32 s37, s37, 0
	s_waitcnt lgkmcnt(0)
	ds_read_b128 v[228:231], v210 offset:0
	ds_read_b128 v[238:241], v211 offset:1024
	s_waitcnt vmcnt(31) lgkmcnt(1)
	v_pk_add_f32 v[130:131], v[228:229], v[130:131]
	v_pk_add_f32 v[132:133], v[230:231], v[132:133]
	v_pk_mul_f32 v[232:233], v[130:131], v[130:131]
	v_pk_mul_f32 v[234:235], v[132:133], v[132:133]
	ds_read_b128 v[228:231], v215 offset:2048
	v_add_f32_e32 v236, v232, v233
	v_add_f32_e32 v236, v234, v236
	v_add_f32_e32 v236, v235, v236
	global_store_dwordx4 v247, v[130:133], s[38:39]
	v_cvt_pk_bf16_f32 v232, v130, v131
	v_cvt_pk_bf16_f32 v233, v132, v133
	v_add_f32_dpp v236, v236, v236 quad_perm:[1,0,3,2] row_mask:0xf bank_mask:0xf
	global_store_dwordx2 v248, v[232:233], s[50:51]
	s_add_u32 s38, s38, 0x4000
	s_addc_u32 s39, s39, 0
	v_add_f32_dpp v236, v236, v236 quad_perm:[2,3,0,1] row_mask:0xf bank_mask:0xf
	s_add_u32 s50, s50, 0x2000
	s_addc_u32 s51, s51, 0
	v_add_f32_dpp v236, v236, v236 row_half_mirror row_mask:0xf bank_mask:0xf
	s_nop 1
	v_add_f32_dpp v236, v236, v236 row_mirror row_mask:0xf bank_mask:0xf
	s_mov_b64 exec, s[48:49]
	global_store_dword v249, v236, s[34:35] offset:0
	s_mov_b64 exec, -1
	s_waitcnt vmcnt(33) lgkmcnt(1)
	v_pk_add_f32 v[134:135], v[238:239], v[134:135]
	v_pk_add_f32 v[136:137], v[240:241], v[136:137]
	v_pk_mul_f32 v[242:243], v[134:135], v[134:135]
	v_pk_mul_f32 v[244:245], v[136:137], v[136:137]
	ds_read_b128 v[238:241], v237 offset:3072
	v_add_f32_e32 v246, v242, v243
	v_add_f32_e32 v246, v244, v246
	v_add_f32_e32 v246, v245, v246
	global_store_dwordx4 v247, v[134:137], s[38:39]
	v_cvt_pk_bf16_f32 v242, v134, v135
	v_cvt_pk_bf16_f32 v243, v136, v137
	v_add_f32_dpp v246, v246, v246 quad_perm:[1,0,3,2] row_mask:0xf bank_mask:0xf
	global_store_dwordx2 v248, v[242:243], s[50:51]
	s_add_u32 s38, s38, 0x4000
	s_addc_u32 s39, s39, 0
	v_add_f32_dpp v246, v246, v246 quad_perm:[2,3,0,1] row_mask:0xf bank_mask:0xf
	s_add_u32 s50, s50, 0x2000
	s_addc_u32 s51, s51, 0
	v_add_f32_dpp v246, v246, v246 row_half_mirror row_mask:0xf bank_mask:0xf
	s_nop 1
	v_add_f32_dpp v246, v246, v246 row_mirror row_mask:0xf bank_mask:0xf
	s_mov_b64 exec, s[48:49]
	global_store_dword v249, v246, s[34:35] offset:256
	s_mov_b64 exec, -1
	s_waitcnt vmcnt(35) lgkmcnt(1)
	v_pk_add_f32 v[138:139], v[228:229], v[138:139]
	v_pk_add_f32 v[140:141], v[230:231], v[140:141]
	v_pk_mul_f32 v[232:233], v[138:139], v[138:139]
	v_pk_mul_f32 v[234:235], v[140:141], v[140:141]
	ds_read_b128 v[228:231], v210 offset:4096
	v_add_f32_e32 v236, v232, v233
	v_add_f32_e32 v236, v234, v236
	v_add_f32_e32 v236, v235, v236
	global_store_dwordx4 v247, v[138:141], s[38:39]
	v_cvt_pk_bf16_f32 v232, v138, v139
	v_cvt_pk_bf16_f32 v233, v140, v141
	v_add_f32_dpp v236, v236, v236 quad_perm:[1,0,3,2] row_mask:0xf bank_mask:0xf
	global_store_dwordx2 v248, v[232:233], s[50:51]
	s_add_u32 s38, s38, 0x4000
	s_addc_u32 s39, s39, 0
	v_add_f32_dpp v236, v236, v236 quad_perm:[2,3,0,1] row_mask:0xf bank_mask:0xf
	s_add_u32 s50, s50, 0x2000
	s_addc_u32 s51, s51, 0
	v_add_f32_dpp v236, v236, v236 row_half_mirror row_mask:0xf bank_mask:0xf
	s_nop 1
	v_add_f32_dpp v236, v236, v236 row_mirror row_mask:0xf bank_mask:0xf
	s_mov_b64 exec, s[48:49]
	global_store_dword v249, v236, s[34:35] offset:512
	s_mov_b64 exec, -1
	s_waitcnt vmcnt(37) lgkmcnt(1)
	v_pk_add_f32 v[142:143], v[238:239], v[142:143]
	v_pk_add_f32 v[144:145], v[240:241], v[144:145]
	v_pk_mul_f32 v[242:243], v[142:143], v[142:143]
	v_pk_mul_f32 v[244:245], v[144:145], v[144:145]
	ds_read_b128 v[238:241], v211 offset:5120
	v_add_f32_e32 v246, v242, v243
	v_add_f32_e32 v246, v244, v246
	v_add_f32_e32 v246, v245, v246
	global_store_dwordx4 v247, v[142:145], s[38:39]
	v_cvt_pk_bf16_f32 v242, v142, v143
	v_cvt_pk_bf16_f32 v243, v144, v145
	v_add_f32_dpp v246, v246, v246 quad_perm:[1,0,3,2] row_mask:0xf bank_mask:0xf
	global_store_dwordx2 v248, v[242:243], s[50:51]
	s_add_u32 s38, s38, 0x4000
	s_addc_u32 s39, s39, 0
	v_add_f32_dpp v246, v246, v246 quad_perm:[2,3,0,1] row_mask:0xf bank_mask:0xf
	s_add_u32 s50, s50, 0x2000
	s_addc_u32 s51, s51, 0
	v_add_f32_dpp v246, v246, v246 row_half_mirror row_mask:0xf bank_mask:0xf
	s_nop 1
	v_add_f32_dpp v246, v246, v246 row_mirror row_mask:0xf bank_mask:0xf
	s_mov_b64 exec, s[48:49]
	global_store_dword v249, v246, s[34:35] offset:768
	s_mov_b64 exec, -1
	s_waitcnt vmcnt(39) lgkmcnt(1)
	v_pk_add_f32 v[146:147], v[228:229], v[146:147]
	v_pk_add_f32 v[148:149], v[230:231], v[148:149]
	v_pk_mul_f32 v[232:233], v[146:147], v[146:147]
	v_pk_mul_f32 v[234:235], v[148:149], v[148:149]
	ds_read_b128 v[228:231], v215 offset:6144
	v_add_f32_e32 v236, v232, v233
	v_add_f32_e32 v236, v234, v236
	v_add_f32_e32 v236, v235, v236
	global_store_dwordx4 v247, v[146:149], s[38:39]
	v_cvt_pk_bf16_f32 v232, v146, v147
	v_cvt_pk_bf16_f32 v233, v148, v149
	v_add_f32_dpp v236, v236, v236 quad_perm:[1,0,3,2] row_mask:0xf bank_mask:0xf
	global_store_dwordx2 v248, v[232:233], s[50:51]
	s_add_u32 s38, s38, 0x4000
	s_addc_u32 s39, s39, 0
	v_add_f32_dpp v236, v236, v236 quad_perm:[2,3,0,1] row_mask:0xf bank_mask:0xf
	s_add_u32 s50, s50, 0x2000
	s_addc_u32 s51, s51, 0
	v_add_f32_dpp v236, v236, v236 row_half_mirror row_mask:0xf bank_mask:0xf
	s_nop 1
	v_add_f32_dpp v236, v236, v236 row_mirror row_mask:0xf bank_mask:0xf
	s_mov_b64 exec, s[48:49]
	global_store_dword v249, v236, s[34:35] offset:1024
	s_mov_b64 exec, -1
	s_waitcnt vmcnt(41) lgkmcnt(1)
	v_pk_add_f32 v[150:151], v[238:239], v[150:151]
	v_pk_add_f32 v[152:153], v[240:241], v[152:153]
	v_pk_mul_f32 v[242:243], v[150:151], v[150:151]
	v_pk_mul_f32 v[244:245], v[152:153], v[152:153]
	ds_read_b128 v[238:241], v237 offset:7168
	v_add_f32_e32 v246, v242, v243
	v_add_f32_e32 v246, v244, v246
	v_add_f32_e32 v246, v245, v246
	global_store_dwordx4 v247, v[150:153], s[38:39]
	v_cvt_pk_bf16_f32 v242, v150, v151
	v_cvt_pk_bf16_f32 v243, v152, v153
	v_add_f32_dpp v246, v246, v246 quad_perm:[1,0,3,2] row_mask:0xf bank_mask:0xf
	global_store_dwordx2 v248, v[242:243], s[50:51]
	s_add_u32 s38, s38, 0x4000
	s_addc_u32 s39, s39, 0
	v_add_f32_dpp v246, v246, v246 quad_perm:[2,3,0,1] row_mask:0xf bank_mask:0xf
	s_add_u32 s50, s50, 0x2000
	s_addc_u32 s51, s51, 0
	v_add_f32_dpp v246, v246, v246 row_half_mirror row_mask:0xf bank_mask:0xf
	s_nop 1
	v_add_f32_dpp v246, v246, v246 row_mirror row_mask:0xf bank_mask:0xf
	s_mov_b64 exec, s[48:49]
	global_store_dword v249, v246, s[34:35] offset:1280
	s_mov_b64 exec, -1
	s_waitcnt vmcnt(43) lgkmcnt(1)
	v_pk_add_f32 v[154:155], v[228:229], v[154:155]
	v_pk_add_f32 v[156:157], v[230:231], v[156:157]
	v_pk_mul_f32 v[232:233], v[154:155], v[154:155]
	v_pk_mul_f32 v[234:235], v[156:157], v[156:157]
	ds_read_b128 v[228:231], v210 offset:8192
	v_add_f32_e32 v236, v232, v233
	v_add_f32_e32 v236, v234, v236
	v_add_f32_e32 v236, v235, v236
	global_store_dwordx4 v247, v[154:157], s[38:39]
	v_cvt_pk_bf16_f32 v232, v154, v155
	v_cvt_pk_bf16_f32 v233, v156, v157
	v_add_f32_dpp v236, v236, v236 quad_perm:[1,0,3,2] row_mask:0xf bank_mask:0xf
	global_store_dwordx2 v248, v[232:233], s[50:51]
	s_add_u32 s38, s38, 0x4000
	s_addc_u32 s39, s39, 0
	v_add_f32_dpp v236, v236, v236 quad_perm:[2,3,0,1] row_mask:0xf bank_mask:0xf
	s_add_u32 s50, s50, 0x2000
	s_addc_u32 s51, s51, 0
	v_add_f32_dpp v236, v236, v236 row_half_mirror row_mask:0xf bank_mask:0xf
	s_nop 1
	v_add_f32_dpp v236, v236, v236 row_mirror row_mask:0xf bank_mask:0xf
	s_mov_b64 exec, s[48:49]
	global_store_dword v249, v236, s[34:35] offset:1536
	s_mov_b64 exec, -1
	s_waitcnt vmcnt(45) lgkmcnt(1)
	v_pk_add_f32 v[158:159], v[238:239], v[158:159]
	v_pk_add_f32 v[160:161], v[240:241], v[160:161]
	v_pk_mul_f32 v[242:243], v[158:159], v[158:159]
	v_pk_mul_f32 v[244:245], v[160:161], v[160:161]
	ds_read_b128 v[238:241], v211 offset:9216
	v_add_f32_e32 v246, v242, v243
	v_add_f32_e32 v246, v244, v246
	v_add_f32_e32 v246, v245, v246
	global_store_dwordx4 v247, v[158:161], s[38:39]
	v_cvt_pk_bf16_f32 v242, v158, v159
	v_cvt_pk_bf16_f32 v243, v160, v161
	v_add_f32_dpp v246, v246, v246 quad_perm:[1,0,3,2] row_mask:0xf bank_mask:0xf
	global_store_dwordx2 v248, v[242:243], s[50:51]
	s_add_u32 s38, s38, 0x4000
	s_addc_u32 s39, s39, 0
	v_add_f32_dpp v246, v246, v246 quad_perm:[2,3,0,1] row_mask:0xf bank_mask:0xf
	s_add_u32 s50, s50, 0x2000
	s_addc_u32 s51, s51, 0
	v_add_f32_dpp v246, v246, v246 row_half_mirror row_mask:0xf bank_mask:0xf
	s_nop 1
	v_add_f32_dpp v246, v246, v246 row_mirror row_mask:0xf bank_mask:0xf
	s_mov_b64 exec, s[48:49]
	global_store_dword v249, v246, s[34:35] offset:1792
	s_mov_b64 exec, -1
	s_waitcnt vmcnt(47) lgkmcnt(1)
	v_pk_add_f32 v[162:163], v[228:229], v[162:163]
	v_pk_add_f32 v[164:165], v[230:231], v[164:165]
	v_pk_mul_f32 v[232:233], v[162:163], v[162:163]
	v_pk_mul_f32 v[234:235], v[164:165], v[164:165]
	ds_read_b128 v[228:231], v215 offset:10240
	v_add_f32_e32 v236, v232, v233
	v_add_f32_e32 v236, v234, v236
	v_add_f32_e32 v236, v235, v236
	global_store_dwordx4 v247, v[162:165], s[38:39]
	v_cvt_pk_bf16_f32 v232, v162, v163
	v_cvt_pk_bf16_f32 v233, v164, v165
	v_add_f32_dpp v236, v236, v236 quad_perm:[1,0,3,2] row_mask:0xf bank_mask:0xf
	global_store_dwordx2 v248, v[232:233], s[50:51]
	s_add_u32 s38, s38, 0x4000
	s_addc_u32 s39, s39, 0
	v_add_f32_dpp v236, v236, v236 quad_perm:[2,3,0,1] row_mask:0xf bank_mask:0xf
	s_add_u32 s50, s50, 0x2000
	s_addc_u32 s51, s51, 0
	v_add_f32_dpp v236, v236, v236 row_half_mirror row_mask:0xf bank_mask:0xf
	s_nop 1
	v_add_f32_dpp v236, v236, v236 row_mirror row_mask:0xf bank_mask:0xf
	s_mov_b64 exec, s[48:49]
	global_store_dword v249, v236, s[34:35] offset:2048
	s_mov_b64 exec, -1
	s_waitcnt vmcnt(49) lgkmcnt(1)
	v_pk_add_f32 v[166:167], v[238:239], v[166:167]
	v_pk_add_f32 v[168:169], v[240:241], v[168:169]
	v_pk_mul_f32 v[242:243], v[166:167], v[166:167]
	v_pk_mul_f32 v[244:245], v[168:169], v[168:169]
	ds_read_b128 v[238:241], v237 offset:11264
	v_add_f32_e32 v246, v242, v243
	v_add_f32_e32 v246, v244, v246
	v_add_f32_e32 v246, v245, v246
	global_store_dwordx4 v247, v[166:169], s[38:39]
	v_cvt_pk_bf16_f32 v242, v166, v167
	v_cvt_pk_bf16_f32 v243, v168, v169
	v_add_f32_dpp v246, v246, v246 quad_perm:[1,0,3,2] row_mask:0xf bank_mask:0xf
	global_store_dwordx2 v248, v[242:243], s[50:51]
	s_add_u32 s38, s38, 0x4000
	s_addc_u32 s39, s39, 0
	v_add_f32_dpp v246, v246, v246 quad_perm:[2,3,0,1] row_mask:0xf bank_mask:0xf
	s_add_u32 s50, s50, 0x2000
	s_addc_u32 s51, s51, 0
	v_add_f32_dpp v246, v246, v246 row_half_mirror row_mask:0xf bank_mask:0xf
	s_nop 1
	v_add_f32_dpp v246, v246, v246 row_mirror row_mask:0xf bank_mask:0xf
	s_mov_b64 exec, s[48:49]
	global_store_dword v249, v246, s[34:35] offset:2304
	s_mov_b64 exec, -1
	s_waitcnt vmcnt(51) lgkmcnt(1)
	v_pk_add_f32 v[170:171], v[228:229], v[170:171]
	v_pk_add_f32 v[172:173], v[230:231], v[172:173]
	v_pk_mul_f32 v[232:233], v[170:171], v[170:171]
	v_pk_mul_f32 v[234:235], v[172:173], v[172:173]
	ds_read_b128 v[228:231], v210 offset:12288
	v_add_f32_e32 v236, v232, v233
	v_add_f32_e32 v236, v234, v236
	v_add_f32_e32 v236, v235, v236
	global_store_dwordx4 v247, v[170:173], s[38:39]
	v_cvt_pk_bf16_f32 v232, v170, v171
	v_cvt_pk_bf16_f32 v233, v172, v173
	v_add_f32_dpp v236, v236, v236 quad_perm:[1,0,3,2] row_mask:0xf bank_mask:0xf
	global_store_dwordx2 v248, v[232:233], s[50:51]
	s_add_u32 s38, s38, 0x4000
	s_addc_u32 s39, s39, 0
	v_add_f32_dpp v236, v236, v236 quad_perm:[2,3,0,1] row_mask:0xf bank_mask:0xf
	s_add_u32 s50, s50, 0x2000
	s_addc_u32 s51, s51, 0
	v_add_f32_dpp v236, v236, v236 row_half_mirror row_mask:0xf bank_mask:0xf
	s_nop 1
	v_add_f32_dpp v236, v236, v236 row_mirror row_mask:0xf bank_mask:0xf
	s_mov_b64 exec, s[48:49]
	global_store_dword v249, v236, s[34:35] offset:2560
	s_mov_b64 exec, -1
	s_waitcnt vmcnt(53) lgkmcnt(1)
	v_pk_add_f32 v[188:189], v[238:239], v[188:189]
	v_pk_add_f32 v[190:191], v[240:241], v[190:191]
	v_pk_mul_f32 v[242:243], v[188:189], v[188:189]
	v_pk_mul_f32 v[244:245], v[190:191], v[190:191]
	ds_read_b128 v[238:241], v211 offset:13312
	v_add_f32_e32 v246, v242, v243
	v_add_f32_e32 v246, v244, v246
	v_add_f32_e32 v246, v245, v246
	global_store_dwordx4 v247, v[188:191], s[38:39]
	v_cvt_pk_bf16_f32 v242, v188, v189
	v_cvt_pk_bf16_f32 v243, v190, v191
	v_add_f32_dpp v246, v246, v246 quad_perm:[1,0,3,2] row_mask:0xf bank_mask:0xf
	global_store_dwordx2 v248, v[242:243], s[50:51]
	s_add_u32 s38, s38, 0x4000
	s_addc_u32 s39, s39, 0
	v_add_f32_dpp v246, v246, v246 quad_perm:[2,3,0,1] row_mask:0xf bank_mask:0xf
	s_add_u32 s50, s50, 0x2000
	s_addc_u32 s51, s51, 0
	v_add_f32_dpp v246, v246, v246 row_half_mirror row_mask:0xf bank_mask:0xf
	s_nop 1
	v_add_f32_dpp v246, v246, v246 row_mirror row_mask:0xf bank_mask:0xf
	s_mov_b64 exec, s[48:49]
	global_store_dword v249, v246, s[34:35] offset:2816
	s_mov_b64 exec, -1
	s_waitcnt vmcnt(55) lgkmcnt(1)
	v_pk_add_f32 v[200:201], v[228:229], v[200:201]
	v_pk_add_f32 v[202:203], v[230:231], v[202:203]
	v_pk_mul_f32 v[232:233], v[200:201], v[200:201]
	v_pk_mul_f32 v[234:235], v[202:203], v[202:203]
	ds_read_b128 v[228:231], v215 offset:14336
	v_add_f32_e32 v236, v232, v233
	v_add_f32_e32 v236, v234, v236
	v_add_f32_e32 v236, v235, v236
	global_store_dwordx4 v247, v[200:203], s[38:39]
	v_cvt_pk_bf16_f32 v232, v200, v201
	v_cvt_pk_bf16_f32 v233, v202, v203
	v_add_f32_dpp v236, v236, v236 quad_perm:[1,0,3,2] row_mask:0xf bank_mask:0xf
	global_store_dwordx2 v248, v[232:233], s[50:51]
	s_add_u32 s38, s38, 0x4000
	s_addc_u32 s39, s39, 0
	v_add_f32_dpp v236, v236, v236 quad_perm:[2,3,0,1] row_mask:0xf bank_mask:0xf
	s_add_u32 s50, s50, 0x2000
	s_addc_u32 s51, s51, 0
	v_add_f32_dpp v236, v236, v236 row_half_mirror row_mask:0xf bank_mask:0xf
	s_nop 1
	v_add_f32_dpp v236, v236, v236 row_mirror row_mask:0xf bank_mask:0xf
	s_mov_b64 exec, s[48:49]
	global_store_dword v249, v236, s[34:35] offset:3072
	s_mov_b64 exec, -1
	s_waitcnt vmcnt(57) lgkmcnt(1)
	v_pk_add_f32 v[216:217], v[238:239], v[216:217]
	v_pk_add_f32 v[218:219], v[240:241], v[218:219]
	v_pk_mul_f32 v[242:243], v[216:217], v[216:217]
	v_pk_mul_f32 v[244:245], v[218:219], v[218:219]
	ds_read_b128 v[238:241], v237 offset:15360
	v_add_f32_e32 v246, v242, v243
	v_add_f32_e32 v246, v244, v246
	v_add_f32_e32 v246, v245, v246
	global_store_dwordx4 v247, v[216:219], s[38:39]
	v_cvt_pk_bf16_f32 v242, v216, v217
	v_cvt_pk_bf16_f32 v243, v218, v219
	v_add_f32_dpp v246, v246, v246 quad_perm:[1,0,3,2] row_mask:0xf bank_mask:0xf
	global_store_dwordx2 v248, v[242:243], s[50:51]
	s_add_u32 s38, s38, 0x4000
	s_addc_u32 s39, s39, 0
	v_add_f32_dpp v246, v246, v246 quad_perm:[2,3,0,1] row_mask:0xf bank_mask:0xf
	s_add_u32 s50, s50, 0x2000
	s_addc_u32 s51, s51, 0
	v_add_f32_dpp v246, v246, v246 row_half_mirror row_mask:0xf bank_mask:0xf
	s_nop 1
	v_add_f32_dpp v246, v246, v246 row_mirror row_mask:0xf bank_mask:0xf
	s_mov_b64 exec, s[48:49]
	global_store_dword v249, v246, s[34:35] offset:3328
	s_mov_b64 exec, -1
	s_waitcnt vmcnt(59) lgkmcnt(1)
	v_pk_add_f32 v[220:221], v[228:229], v[220:221]
	v_pk_add_f32 v[222:223], v[230:231], v[222:223]
	v_pk_mul_f32 v[232:233], v[220:221], v[220:221]
	v_pk_mul_f32 v[234:235], v[222:223], v[222:223]
	v_add_f32_e32 v236, v232, v233
	v_add_f32_e32 v236, v234, v236
	v_add_f32_e32 v236, v235, v236
	global_store_dwordx4 v247, v[220:223], s[38:39]
	v_cvt_pk_bf16_f32 v232, v220, v221
	v_cvt_pk_bf16_f32 v233, v222, v223
	v_add_f32_dpp v236, v236, v236 quad_perm:[1,0,3,2] row_mask:0xf bank_mask:0xf
	global_store_dwordx2 v248, v[232:233], s[50:51]
	s_add_u32 s38, s38, 0x4000
	s_addc_u32 s39, s39, 0
	v_add_f32_dpp v236, v236, v236 quad_perm:[2,3,0,1] row_mask:0xf bank_mask:0xf
	s_add_u32 s50, s50, 0x2000
	s_addc_u32 s51, s51, 0
	v_add_f32_dpp v236, v236, v236 row_half_mirror row_mask:0xf bank_mask:0xf
	s_nop 1
	v_add_f32_dpp v236, v236, v236 row_mirror row_mask:0xf bank_mask:0xf
	s_mov_b64 exec, s[48:49]
	global_store_dword v249, v236, s[34:35] offset:3584
	s_mov_b64 exec, -1
	s_waitcnt vmcnt(61) lgkmcnt(0)
	v_pk_add_f32 v[224:225], v[238:239], v[224:225]
	v_pk_add_f32 v[226:227], v[240:241], v[226:227]
	v_pk_mul_f32 v[242:243], v[224:225], v[224:225]
	v_pk_mul_f32 v[244:245], v[226:227], v[226:227]
	v_add_f32_e32 v246, v242, v243
	v_add_f32_e32 v246, v244, v246
	v_add_f32_e32 v246, v245, v246
	global_store_dwordx4 v247, v[224:227], s[38:39]
	v_cvt_pk_bf16_f32 v242, v224, v225
	v_cvt_pk_bf16_f32 v243, v226, v227
	v_add_f32_dpp v246, v246, v246 quad_perm:[1,0,3,2] row_mask:0xf bank_mask:0xf
	global_store_dwordx2 v248, v[242:243], s[50:51]
	s_add_u32 s38, s38, 0x4000
	s_addc_u32 s39, s39, 0
	v_add_f32_dpp v246, v246, v246 quad_perm:[2,3,0,1] row_mask:0xf bank_mask:0xf
	s_add_u32 s50, s50, 0x2000
	s_addc_u32 s51, s51, 0
	v_add_f32_dpp v246, v246, v246 row_half_mirror row_mask:0xf bank_mask:0xf
	s_nop 1
	v_add_f32_dpp v246, v246, v246 row_mirror row_mask:0xf bank_mask:0xf
	s_mov_b64 exec, s[48:49]
	global_store_dword v249, v246, s[34:35] offset:3840
	s_mov_b64 exec, -1
	s_add_u32 s34, s34, 0x1000
	s_addc_u32 s35, s35, 0
	v_and_b32_e32 v238, 15, v198
	v_xor_b32_e32 v238, v238, v199
	v_lshl_add_u32 v239, v198, 8, s40
	v_xor_b32_e32 v228, 0, v238
	v_lshl_add_u32 v228, v228, 4, v239
	v_xor_b32_e32 v229, 2, v238
	v_lshl_add_u32 v229, v229, 4, v239
	v_xor_b32_e32 v230, 4, v238
	v_lshl_add_u32 v230, v230, 4, v239
	v_xor_b32_e32 v231, 6, v238
	v_lshl_add_u32 v231, v231, 4, v239
	v_xor_b32_e32 v232, 8, v238
	v_lshl_add_u32 v232, v232, 4, v239
	v_xor_b32_e32 v233, 10, v238
	v_lshl_add_u32 v233, v233, 4, v239
	v_xor_b32_e32 v234, 12, v238
	v_lshl_add_u32 v234, v234, 4, v239
	v_xor_b32_e32 v235, 14, v238
	v_lshl_add_u32 v235, v235, 4, v239
	ds_write_b128 v228, v[18:21]
	ds_write_b128 v229, v[22:25]
	ds_write_b128 v230, v[26:29]
	ds_write_b128 v231, v[30:33]
	ds_write_b128 v232, v[50:53]
	ds_write_b128 v233, v[54:57]
	ds_write_b128 v234, v[58:61]
	ds_write_b128 v235, v[62:65]
	ds_write_b128 v228, v[2:5] offset:8192
	ds_write_b128 v229, v[6:9] offset:8192
	ds_write_b128 v230, v[10:13] offset:8192
	ds_write_b128 v231, v[14:17] offset:8192
	ds_write_b128 v232, v[34:37] offset:8192
	ds_write_b128 v233, v[38:41] offset:8192
	ds_write_b128 v234, v[42:45] offset:8192
	ds_write_b128 v235, v[46:49] offset:8192
	s_waitcnt lgkmcnt(0)
	ds_read_b128 v[228:231], v210 offset:0
	ds_read_b128 v[238:241], v211 offset:1024
	s_waitcnt vmcnt(63) lgkmcnt(1)
	v_pk_add_f32 v[82:83], v[228:229], v[82:83]
	v_pk_add_f32 v[84:85], v[230:231], v[84:85]
	v_pk_mul_f32 v[232:233], v[82:83], v[82:83]
	v_pk_mul_f32 v[234:235], v[84:85], v[84:85]
	ds_read_b128 v[228:231], v215 offset:2048
	v_add_f32_e32 v236, v232, v233
	v_add_f32_e32 v236, v234, v236
	v_add_f32_e32 v236, v235, v236
	global_store_dwordx4 v247, v[82:85], s[38:39]
	v_cvt_pk_bf16_f32 v232, v82, v83
	v_cvt_pk_bf16_f32 v233, v84, v85
	v_add_f32_dpp v236, v236, v236 quad_perm:[1,0,3,2] row_mask:0xf bank_mask:0xf
	global_store_dwordx2 v248, v[232:233], s[50:51]
	s_add_u32 s38, s38, 0x4000
	s_addc_u32 s39, s39, 0
	v_add_f32_dpp v236, v236, v236 quad_perm:[2,3,0,1] row_mask:0xf bank_mask:0xf
	s_add_u32 s50, s50, 0x2000
	s_addc_u32 s51, s51, 0
	v_add_f32_dpp v236, v236, v236 row_half_mirror row_mask:0xf bank_mask:0xf
	s_nop 1
	v_add_f32_dpp v236, v236, v236 row_mirror row_mask:0xf bank_mask:0xf
	s_mov_b64 exec, s[48:49]
	global_store_dword v249, v236, s[34:35] offset:0
	s_mov_b64 exec, -1
	s_waitcnt vmcnt(63) lgkmcnt(1)
	v_pk_add_f32 v[86:87], v[238:239], v[86:87]
	v_pk_add_f32 v[88:89], v[240:241], v[88:89]
	v_pk_mul_f32 v[242:243], v[86:87], v[86:87]
	v_pk_mul_f32 v[244:245], v[88:89], v[88:89]
	ds_read_b128 v[238:241], v237 offset:3072
	v_add_f32_e32 v246, v242, v243
	v_add_f32_e32 v246, v244, v246
	v_add_f32_e32 v246, v245, v246
	global_store_dwordx4 v247, v[86:89], s[38:39]
	v_cvt_pk_bf16_f32 v242, v86, v87
	v_cvt_pk_bf16_f32 v243, v88, v89
	v_add_f32_dpp v246, v246, v246 quad_perm:[1,0,3,2] row_mask:0xf bank_mask:0xf
	global_store_dwordx2 v248, v[242:243], s[50:51]
	s_add_u32 s38, s38, 0x4000
	s_addc_u32 s39, s39, 0
	v_add_f32_dpp v246, v246, v246 quad_perm:[2,3,0,1] row_mask:0xf bank_mask:0xf
	s_add_u32 s50, s50, 0x2000
	s_addc_u32 s51, s51, 0
	v_add_f32_dpp v246, v246, v246 row_half_mirror row_mask:0xf bank_mask:0xf
	s_nop 1
	v_add_f32_dpp v246, v246, v246 row_mirror row_mask:0xf bank_mask:0xf
	s_mov_b64 exec, s[48:49]
	global_store_dword v249, v246, s[34:35] offset:256
	s_mov_b64 exec, -1
	s_waitcnt vmcnt(63) lgkmcnt(1)
	v_pk_add_f32 v[90:91], v[228:229], v[90:91]
	v_pk_add_f32 v[92:93], v[230:231], v[92:93]
	v_pk_mul_f32 v[232:233], v[90:91], v[90:91]
	v_pk_mul_f32 v[234:235], v[92:93], v[92:93]
	ds_read_b128 v[228:231], v210 offset:4096
	v_add_f32_e32 v236, v232, v233
	v_add_f32_e32 v236, v234, v236
	v_add_f32_e32 v236, v235, v236
	global_store_dwordx4 v247, v[90:93], s[38:39]
	v_cvt_pk_bf16_f32 v232, v90, v91
	v_cvt_pk_bf16_f32 v233, v92, v93
	v_add_f32_dpp v236, v236, v236 quad_perm:[1,0,3,2] row_mask:0xf bank_mask:0xf
	global_store_dwordx2 v248, v[232:233], s[50:51]
	s_add_u32 s38, s38, 0x4000
	s_addc_u32 s39, s39, 0
	v_add_f32_dpp v236, v236, v236 quad_perm:[2,3,0,1] row_mask:0xf bank_mask:0xf
	s_add_u32 s50, s50, 0x2000
	s_addc_u32 s51, s51, 0
	v_add_f32_dpp v236, v236, v236 row_half_mirror row_mask:0xf bank_mask:0xf
	s_nop 1
	v_add_f32_dpp v236, v236, v236 row_mirror row_mask:0xf bank_mask:0xf
	s_mov_b64 exec, s[48:49]
	global_store_dword v249, v236, s[34:35] offset:512
	s_mov_b64 exec, -1
	s_waitcnt vmcnt(63) lgkmcnt(1)
	v_pk_add_f32 v[94:95], v[238:239], v[94:95]
	v_pk_add_f32 v[96:97], v[240:241], v[96:97]
	v_pk_mul_f32 v[242:243], v[94:95], v[94:95]
	v_pk_mul_f32 v[244:245], v[96:97], v[96:97]
	ds_read_b128 v[238:241], v211 offset:5120
	v_add_f32_e32 v246, v242, v243
	v_add_f32_e32 v246, v244, v246
	v_add_f32_e32 v246, v245, v246
	global_store_dwordx4 v247, v[94:97], s[38:39]
	v_cvt_pk_bf16_f32 v242, v94, v95
	v_cvt_pk_bf16_f32 v243, v96, v97
	v_add_f32_dpp v246, v246, v246 quad_perm:[1,0,3,2] row_mask:0xf bank_mask:0xf
	global_store_dwordx2 v248, v[242:243], s[50:51]
	s_add_u32 s38, s38, 0x4000
	s_addc_u32 s39, s39, 0
	v_add_f32_dpp v246, v246, v246 quad_perm:[2,3,0,1] row_mask:0xf bank_mask:0xf
	s_add_u32 s50, s50, 0x2000
	s_addc_u32 s51, s51, 0
	v_add_f32_dpp v246, v246, v246 row_half_mirror row_mask:0xf bank_mask:0xf
	s_nop 1
	v_add_f32_dpp v246, v246, v246 row_mirror row_mask:0xf bank_mask:0xf
	s_mov_b64 exec, s[48:49]
	global_store_dword v249, v246, s[34:35] offset:768
	s_mov_b64 exec, -1
	s_waitcnt vmcnt(63) lgkmcnt(1)
	v_pk_add_f32 v[114:115], v[228:229], v[114:115]
	v_pk_add_f32 v[116:117], v[230:231], v[116:117]
	v_pk_mul_f32 v[232:233], v[114:115], v[114:115]
	v_pk_mul_f32 v[234:235], v[116:117], v[116:117]
	ds_read_b128 v[228:231], v215 offset:6144
	v_add_f32_e32 v236, v232, v233
	v_add_f32_e32 v236, v234, v236
	v_add_f32_e32 v236, v235, v236
	global_store_dwordx4 v247, v[114:117], s[38:39]
	v_cvt_pk_bf16_f32 v232, v114, v115
	v_cvt_pk_bf16_f32 v233, v116, v117
	v_add_f32_dpp v236, v236, v236 quad_perm:[1,0,3,2] row_mask:0xf bank_mask:0xf
	global_store_dwordx2 v248, v[232:233], s[50:51]
	s_add_u32 s38, s38, 0x4000
	s_addc_u32 s39, s39, 0
	v_add_f32_dpp v236, v236, v236 quad_perm:[2,3,0,1] row_mask:0xf bank_mask:0xf
	s_add_u32 s50, s50, 0x2000
	s_addc_u32 s51, s51, 0
	v_add_f32_dpp v236, v236, v236 row_half_mirror row_mask:0xf bank_mask:0xf
	s_nop 1
	v_add_f32_dpp v236, v236, v236 row_mirror row_mask:0xf bank_mask:0xf
	s_mov_b64 exec, s[48:49]
	global_store_dword v249, v236, s[34:35] offset:1024
	s_mov_b64 exec, -1
	s_waitcnt vmcnt(63) lgkmcnt(1)
	v_pk_add_f32 v[118:119], v[238:239], v[118:119]
	v_pk_add_f32 v[120:121], v[240:241], v[120:121]
	v_pk_mul_f32 v[242:243], v[118:119], v[118:119]
	v_pk_mul_f32 v[244:245], v[120:121], v[120:121]
	ds_read_b128 v[238:241], v237 offset:7168
	v_add_f32_e32 v246, v242, v243
	v_add_f32_e32 v246, v244, v246
	v_add_f32_e32 v246, v245, v246
	global_store_dwordx4 v247, v[118:121], s[38:39]
	v_cvt_pk_bf16_f32 v242, v118, v119
	v_cvt_pk_bf16_f32 v243, v120, v121
	v_add_f32_dpp v246, v246, v246 quad_perm:[1,0,3,2] row_mask:0xf bank_mask:0xf
	global_store_dwordx2 v248, v[242:243], s[50:51]
	s_add_u32 s38, s38, 0x4000
	s_addc_u32 s39, s39, 0
	v_add_f32_dpp v246, v246, v246 quad_perm:[2,3,0,1] row_mask:0xf bank_mask:0xf
	s_add_u32 s50, s50, 0x2000
	s_addc_u32 s51, s51, 0
	v_add_f32_dpp v246, v246, v246 row_half_mirror row_mask:0xf bank_mask:0xf
	s_nop 1
	v_add_f32_dpp v246, v246, v246 row_mirror row_mask:0xf bank_mask:0xf
	s_mov_b64 exec, s[48:49]
	global_store_dword v249, v246, s[34:35] offset:1280
	s_mov_b64 exec, -1
	s_waitcnt vmcnt(63) lgkmcnt(1)
	v_pk_add_f32 v[122:123], v[228:229], v[122:123]
	v_pk_add_f32 v[124:125], v[230:231], v[124:125]
	v_pk_mul_f32 v[232:233], v[122:123], v[122:123]
	v_pk_mul_f32 v[234:235], v[124:125], v[124:125]
	ds_read_b128 v[228:231], v210 offset:8192
	v_add_f32_e32 v236, v232, v233
	v_add_f32_e32 v236, v234, v236
	v_add_f32_e32 v236, v235, v236
	global_store_dwordx4 v247, v[122:125], s[38:39]
	v_cvt_pk_bf16_f32 v232, v122, v123
	v_cvt_pk_bf16_f32 v233, v124, v125
	v_add_f32_dpp v236, v236, v236 quad_perm:[1,0,3,2] row_mask:0xf bank_mask:0xf
	global_store_dwordx2 v248, v[232:233], s[50:51]
	s_add_u32 s38, s38, 0x4000
	s_addc_u32 s39, s39, 0
	v_add_f32_dpp v236, v236, v236 quad_perm:[2,3,0,1] row_mask:0xf bank_mask:0xf
	s_add_u32 s50, s50, 0x2000
	s_addc_u32 s51, s51, 0
	v_add_f32_dpp v236, v236, v236 row_half_mirror row_mask:0xf bank_mask:0xf
	s_nop 1
	v_add_f32_dpp v236, v236, v236 row_mirror row_mask:0xf bank_mask:0xf
	s_mov_b64 exec, s[48:49]
	global_store_dword v249, v236, s[34:35] offset:1536
	s_mov_b64 exec, -1
	s_waitcnt vmcnt(63) lgkmcnt(1)
	v_pk_add_f32 v[126:127], v[238:239], v[126:127]
	v_pk_add_f32 v[128:129], v[240:241], v[128:129]
	v_pk_mul_f32 v[242:243], v[126:127], v[126:127]
	v_pk_mul_f32 v[244:245], v[128:129], v[128:129]
	ds_read_b128 v[238:241], v211 offset:9216
	v_add_f32_e32 v246, v242, v243
	v_add_f32_e32 v246, v244, v246
	v_add_f32_e32 v246, v245, v246
	global_store_dwordx4 v247, v[126:129], s[38:39]
	v_cvt_pk_bf16_f32 v242, v126, v127
	v_cvt_pk_bf16_f32 v243, v128, v129
	v_add_f32_dpp v246, v246, v246 quad_perm:[1,0,3,2] row_mask:0xf bank_mask:0xf
	global_store_dwordx2 v248, v[242:243], s[50:51]
	s_add_u32 s38, s38, 0x4000
	s_addc_u32 s39, s39, 0
	v_add_f32_dpp v246, v246, v246 quad_perm:[2,3,0,1] row_mask:0xf bank_mask:0xf
	s_add_u32 s50, s50, 0x2000
	s_addc_u32 s51, s51, 0
	v_add_f32_dpp v246, v246, v246 row_half_mirror row_mask:0xf bank_mask:0xf
	s_nop 1
	v_add_f32_dpp v246, v246, v246 row_mirror row_mask:0xf bank_mask:0xf
	s_mov_b64 exec, s[48:49]
	global_store_dword v249, v246, s[34:35] offset:1792
	s_mov_b64 exec, -1
	s_waitcnt vmcnt(63) lgkmcnt(1)
	v_pk_add_f32 v[66:67], v[228:229], v[66:67]
	v_pk_add_f32 v[68:69], v[230:231], v[68:69]
	v_pk_mul_f32 v[232:233], v[66:67], v[66:67]
	v_pk_mul_f32 v[234:235], v[68:69], v[68:69]
	ds_read_b128 v[228:231], v215 offset:10240
	v_add_f32_e32 v236, v232, v233
	v_add_f32_e32 v236, v234, v236
	v_add_f32_e32 v236, v235, v236
	global_store_dwordx4 v247, v[66:69], s[38:39]
	v_cvt_pk_bf16_f32 v232, v66, v67
	v_cvt_pk_bf16_f32 v233, v68, v69
	v_add_f32_dpp v236, v236, v236 quad_perm:[1,0,3,2] row_mask:0xf bank_mask:0xf
	global_store_dwordx2 v248, v[232:233], s[50:51]
	s_add_u32 s38, s38, 0x4000
	s_addc_u32 s39, s39, 0
	v_add_f32_dpp v236, v236, v236 quad_perm:[2,3,0,1] row_mask:0xf bank_mask:0xf
	s_add_u32 s50, s50, 0x2000
	s_addc_u32 s51, s51, 0
	v_add_f32_dpp v236, v236, v236 row_half_mirror row_mask:0xf bank_mask:0xf
	s_nop 1
	v_add_f32_dpp v236, v236, v236 row_mirror row_mask:0xf bank_mask:0xf
	s_mov_b64 exec, s[48:49]
	global_store_dword v249, v236, s[34:35] offset:2048
	s_mov_b64 exec, -1
	s_waitcnt vmcnt(63) lgkmcnt(1)
	v_pk_add_f32 v[70:71], v[238:239], v[70:71]
	v_pk_add_f32 v[72:73], v[240:241], v[72:73]
	v_pk_mul_f32 v[242:243], v[70:71], v[70:71]
	v_pk_mul_f32 v[244:245], v[72:73], v[72:73]
	ds_read_b128 v[238:241], v237 offset:11264
	v_add_f32_e32 v246, v242, v243
	v_add_f32_e32 v246, v244, v246
	v_add_f32_e32 v246, v245, v246
	global_store_dwordx4 v247, v[70:73], s[38:39]
	v_cvt_pk_bf16_f32 v242, v70, v71
	v_cvt_pk_bf16_f32 v243, v72, v73
	v_add_f32_dpp v246, v246, v246 quad_perm:[1,0,3,2] row_mask:0xf bank_mask:0xf
	global_store_dwordx2 v248, v[242:243], s[50:51]
	s_add_u32 s38, s38, 0x4000
	s_addc_u32 s39, s39, 0
	v_add_f32_dpp v246, v246, v246 quad_perm:[2,3,0,1] row_mask:0xf bank_mask:0xf
	s_add_u32 s50, s50, 0x2000
	s_addc_u32 s51, s51, 0
	v_add_f32_dpp v246, v246, v246 row_half_mirror row_mask:0xf bank_mask:0xf
	s_nop 1
	v_add_f32_dpp v246, v246, v246 row_mirror row_mask:0xf bank_mask:0xf
	s_mov_b64 exec, s[48:49]
	global_store_dword v249, v246, s[34:35] offset:2304
	s_mov_b64 exec, -1
	s_waitcnt vmcnt(63) lgkmcnt(1)
	v_pk_add_f32 v[74:75], v[228:229], v[74:75]
	v_pk_add_f32 v[76:77], v[230:231], v[76:77]
	v_pk_mul_f32 v[232:233], v[74:75], v[74:75]
	v_pk_mul_f32 v[234:235], v[76:77], v[76:77]
	ds_read_b128 v[228:231], v210 offset:12288
	v_add_f32_e32 v236, v232, v233
	v_add_f32_e32 v236, v234, v236
	v_add_f32_e32 v236, v235, v236
	global_store_dwordx4 v247, v[74:77], s[38:39]
	v_cvt_pk_bf16_f32 v232, v74, v75
	v_cvt_pk_bf16_f32 v233, v76, v77
	v_add_f32_dpp v236, v236, v236 quad_perm:[1,0,3,2] row_mask:0xf bank_mask:0xf
	global_store_dwordx2 v248, v[232:233], s[50:51]
	s_add_u32 s38, s38, 0x4000
	s_addc_u32 s39, s39, 0
	v_add_f32_dpp v236, v236, v236 quad_perm:[2,3,0,1] row_mask:0xf bank_mask:0xf
	s_add_u32 s50, s50, 0x2000
	s_addc_u32 s51, s51, 0
	v_add_f32_dpp v236, v236, v236 row_half_mirror row_mask:0xf bank_mask:0xf
	s_nop 1
	v_add_f32_dpp v236, v236, v236 row_mirror row_mask:0xf bank_mask:0xf
	s_mov_b64 exec, s[48:49]
	global_store_dword v249, v236, s[34:35] offset:2560
	s_mov_b64 exec, -1
	s_waitcnt vmcnt(63) lgkmcnt(1)
	v_pk_add_f32 v[78:79], v[238:239], v[78:79]
	v_pk_add_f32 v[80:81], v[240:241], v[80:81]
	v_pk_mul_f32 v[242:243], v[78:79], v[78:79]
	v_pk_mul_f32 v[244:245], v[80:81], v[80:81]
	ds_read_b128 v[238:241], v211 offset:13312
	v_add_f32_e32 v246, v242, v243
	v_add_f32_e32 v246, v244, v246
	v_add_f32_e32 v246, v245, v246
	global_store_dwordx4 v247, v[78:81], s[38:39]
	v_cvt_pk_bf16_f32 v242, v78, v79
	v_cvt_pk_bf16_f32 v243, v80, v81
	v_add_f32_dpp v246, v246, v246 quad_perm:[1,0,3,2] row_mask:0xf bank_mask:0xf
	global_store_dwordx2 v248, v[242:243], s[50:51]
	s_add_u32 s38, s38, 0x4000
	s_addc_u32 s39, s39, 0
	v_add_f32_dpp v246, v246, v246 quad_perm:[2,3,0,1] row_mask:0xf bank_mask:0xf
	s_add_u32 s50, s50, 0x2000
	s_addc_u32 s51, s51, 0
	v_add_f32_dpp v246, v246, v246 row_half_mirror row_mask:0xf bank_mask:0xf
	s_nop 1
	v_add_f32_dpp v246, v246, v246 row_mirror row_mask:0xf bank_mask:0xf
	s_mov_b64 exec, s[48:49]
	global_store_dword v249, v246, s[34:35] offset:2816
	s_mov_b64 exec, -1
	s_waitcnt vmcnt(63) lgkmcnt(1)
	v_pk_add_f32 v[98:99], v[228:229], v[98:99]
	v_pk_add_f32 v[100:101], v[230:231], v[100:101]
	v_pk_mul_f32 v[232:233], v[98:99], v[98:99]
	v_pk_mul_f32 v[234:235], v[100:101], v[100:101]
	ds_read_b128 v[228:231], v215 offset:14336
	v_add_f32_e32 v236, v232, v233
	v_add_f32_e32 v236, v234, v236
	v_add_f32_e32 v236, v235, v236
	global_store_dwordx4 v247, v[98:101], s[38:39]
	v_cvt_pk_bf16_f32 v232, v98, v99
	v_cvt_pk_bf16_f32 v233, v100, v101
	v_add_f32_dpp v236, v236, v236 quad_perm:[1,0,3,2] row_mask:0xf bank_mask:0xf
	global_store_dwordx2 v248, v[232:233], s[50:51]
	s_add_u32 s38, s38, 0x4000
	s_addc_u32 s39, s39, 0
	v_add_f32_dpp v236, v236, v236 quad_perm:[2,3,0,1] row_mask:0xf bank_mask:0xf
	s_add_u32 s50, s50, 0x2000
	s_addc_u32 s51, s51, 0
	v_add_f32_dpp v236, v236, v236 row_half_mirror row_mask:0xf bank_mask:0xf
	s_nop 1
	v_add_f32_dpp v236, v236, v236 row_mirror row_mask:0xf bank_mask:0xf
	s_mov_b64 exec, s[48:49]
	global_store_dword v249, v236, s[34:35] offset:3072
	s_mov_b64 exec, -1
	s_waitcnt vmcnt(63) lgkmcnt(1)
	v_pk_add_f32 v[102:103], v[238:239], v[102:103]
	v_pk_add_f32 v[104:105], v[240:241], v[104:105]
	v_pk_mul_f32 v[242:243], v[102:103], v[102:103]
	v_pk_mul_f32 v[244:245], v[104:105], v[104:105]
	ds_read_b128 v[238:241], v237 offset:15360
	v_add_f32_e32 v246, v242, v243
	v_add_f32_e32 v246, v244, v246
	v_add_f32_e32 v246, v245, v246
	global_store_dwordx4 v247, v[102:105], s[38:39]
	v_cvt_pk_bf16_f32 v242, v102, v103
	v_cvt_pk_bf16_f32 v243, v104, v105
	v_add_f32_dpp v246, v246, v246 quad_perm:[1,0,3,2] row_mask:0xf bank_mask:0xf
	global_store_dwordx2 v248, v[242:243], s[50:51]
	s_add_u32 s38, s38, 0x4000
	s_addc_u32 s39, s39, 0
	v_add_f32_dpp v246, v246, v246 quad_perm:[2,3,0,1] row_mask:0xf bank_mask:0xf
	s_add_u32 s50, s50, 0x2000
	s_addc_u32 s51, s51, 0
	v_add_f32_dpp v246, v246, v246 row_half_mirror row_mask:0xf bank_mask:0xf
	s_nop 1
	v_add_f32_dpp v246, v246, v246 row_mirror row_mask:0xf bank_mask:0xf
	s_mov_b64 exec, s[48:49]
	global_store_dword v249, v246, s[34:35] offset:3328
	s_mov_b64 exec, -1
	s_waitcnt vmcnt(63) lgkmcnt(1)
	v_pk_add_f32 v[106:107], v[228:229], v[106:107]
	v_pk_add_f32 v[108:109], v[230:231], v[108:109]
	v_pk_mul_f32 v[232:233], v[106:107], v[106:107]
	v_pk_mul_f32 v[234:235], v[108:109], v[108:109]
	v_add_f32_e32 v236, v232, v233
	v_add_f32_e32 v236, v234, v236
	v_add_f32_e32 v236, v235, v236
	global_store_dwordx4 v247, v[106:109], s[38:39]
	v_cvt_pk_bf16_f32 v232, v106, v107
	v_cvt_pk_bf16_f32 v233, v108, v109
	v_add_f32_dpp v236, v236, v236 quad_perm:[1,0,3,2] row_mask:0xf bank_mask:0xf
	global_store_dwordx2 v248, v[232:233], s[50:51]
	s_add_u32 s38, s38, 0x4000
	s_addc_u32 s39, s39, 0
	v_add_f32_dpp v236, v236, v236 quad_perm:[2,3,0,1] row_mask:0xf bank_mask:0xf
	s_add_u32 s50, s50, 0x2000
	s_addc_u32 s51, s51, 0
	v_add_f32_dpp v236, v236, v236 row_half_mirror row_mask:0xf bank_mask:0xf
	s_nop 1
	v_add_f32_dpp v236, v236, v236 row_mirror row_mask:0xf bank_mask:0xf
	s_mov_b64 exec, s[48:49]
	global_store_dword v249, v236, s[34:35] offset:3584
	s_mov_b64 exec, -1
	s_waitcnt vmcnt(63) lgkmcnt(0)
	v_pk_add_f32 v[110:111], v[238:239], v[110:111]
	v_pk_add_f32 v[112:113], v[240:241], v[112:113]
	v_pk_mul_f32 v[242:243], v[110:111], v[110:111]
	v_pk_mul_f32 v[244:245], v[112:113], v[112:113]
	v_add_f32_e32 v246, v242, v243
	v_add_f32_e32 v246, v244, v246
	v_add_f32_e32 v246, v245, v246
	global_store_dwordx4 v247, v[110:113], s[38:39]
	v_cvt_pk_bf16_f32 v242, v110, v111
	v_cvt_pk_bf16_f32 v243, v112, v113
	v_add_f32_dpp v246, v246, v246 quad_perm:[1,0,3,2] row_mask:0xf bank_mask:0xf
	global_store_dwordx2 v248, v[242:243], s[50:51]
	s_add_u32 s38, s38, 0x4000
	s_addc_u32 s39, s39, 0
	v_add_f32_dpp v246, v246, v246 quad_perm:[2,3,0,1] row_mask:0xf bank_mask:0xf
	s_add_u32 s50, s50, 0x2000
	s_addc_u32 s51, s51, 0
	v_add_f32_dpp v246, v246, v246 row_half_mirror row_mask:0xf bank_mask:0xf
	s_nop 1
	v_add_f32_dpp v246, v246, v246 row_mirror row_mask:0xf bank_mask:0xf
	s_mov_b64 exec, s[48:49]
	global_store_dword v249, v246, s[34:35] offset:3840
	s_mov_b64 exec, -1
	s_waitcnt lgkmcnt(0)
	s_branch .LBB0_1507

.LBB0_1696:
	v_readfirstlane_b32 s40, v204
	s_lshr_b32 s40, s40, 6
	s_and_b32 s41, s40, 1
	s_bfe_u32 s42, s40, 0x10001
	s_lshr_b32 s43, s40, 2
	s_lshl_b32 s44, s4, 1
	s_add_i32 s44, s44, s42
	s_lshl_b32 s45, s44, 7
	s_lshl_b32 s46, s41, 6
	s_add_i32 s45, s45, s46
	s_lshl_b32 s46, s43, 7
	s_add_i32 s46, s46, s2
	s_lshl_b32 s47, s44, 1
	s_add_i32 s47, s47, s41
	v_readlane_b32 s36, v250, 9
	v_readlane_b32 s37, v250, 10
	s_mov_b64 s[38:39], s[36:37]
	v_readlane_b32 s50, v250, 11
	v_readlane_b32 s51, v250, 12
	s_add_u32 s34, s50, 0xf900000
	s_addc_u32 s35, s51, 0
	s_add_u32 s50, s50, 0x5800000
	s_addc_u32 s51, s51, 0
	s_lshl_b32 s48, s46, 12
	s_lshl_b32 s49, s45, 2
	s_add_u32 s48, s48, s49
	s_add_u32 s36, s36, s48
	s_addc_u32 s37, s37, 0
	s_add_u32 s38, s38, s48
	s_addc_u32 s39, s39, 0
	s_lshr_b32 s48, s48, 1
	s_add_u32 s50, s50, s48
	s_addc_u32 s51, s51, 0
	s_lshl_b32 s48, s46, 6
	s_lshl_b32 s49, s47, 2
	s_add_u32 s48, s48, s49
	s_add_u32 s34, s34, s48
	s_addc_u32 s35, s35, 0
	v_and_b32_e32 v249, 63, v204
	v_and_b32_e32 v170, 31, v249
	v_lshrrev_b32_e32 v171, 5, v249
	v_and_b32_e32 v208, 15, v249
	v_lshrrev_b32_e32 v209, 4, v249
	s_lshl_b32 s40, s40, 14
	v_and_b32_e32 v238, 15, v170
	v_xor_b32_e32 v238, v238, v171
	v_lshl_add_u32 v239, v170, 8, s40
	v_xor_b32_e32 v228, 0, v238
	v_lshl_add_u32 v228, v228, 4, v239
	v_xor_b32_e32 v229, 2, v238
	v_lshl_add_u32 v229, v229, 4, v239
	v_xor_b32_e32 v230, 4, v238
	v_lshl_add_u32 v230, v230, 4, v239
	v_xor_b32_e32 v231, 6, v238
	v_lshl_add_u32 v231, v231, 4, v239
	v_xor_b32_e32 v232, 8, v238
	v_lshl_add_u32 v232, v232, 4, v239
	v_xor_b32_e32 v233, 10, v238
	v_lshl_add_u32 v233, v233, 4, v239
	v_xor_b32_e32 v234, 12, v238
	v_lshl_add_u32 v234, v234, 4, v239
	v_xor_b32_e32 v235, 14, v238
	v_lshl_add_u32 v235, v235, 4, v239
	v_lshl_add_u32 v239, v209, 8, s40
	v_add_u32_e32 v210, 0, v209
	v_xor_b32_e32 v210, v210, v208
	v_lshl_add_u32 v210, v210, 4, v239
	v_add_u32_e32 v211, 4, v209
	v_xor_b32_e32 v211, v211, v208
	v_lshl_add_u32 v211, v211, 4, v239
	v_add_u32_e32 v215, 8, v209
	v_xor_b32_e32 v215, v215, v208
	v_lshl_add_u32 v215, v215, 4, v239
	v_add_u32_e32 v237, 12, v209
	v_xor_b32_e32 v237, v237, v208
	v_lshl_add_u32 v237, v237, 4, v239
	v_lshlrev_b32_e32 v247, 12, v209
	v_lshl_add_u32 v247, v208, 4, v247
	v_lshrrev_b32_e32 v248, 1, v247
	v_lshlrev_b32_e32 v249, 6, v209
	s_mov_b32 s48, 0x00010001
	s_mov_b32 s49, 0x00010001
	global_load_dwordx4 v[130:133], v247, s[36:37]
	s_add_u32 s36, s36, 0x4000
	s_addc_u32 s37, s37, 0
	global_load_dwordx4 v[134:137], v247, s[36:37]
	s_add_u32 s36, s36, 0x4000
	s_addc_u32 s37, s37, 0
	global_load_dwordx4 v[138:141], v247, s[36:37]
	s_add_u32 s36, s36, 0x4000
	s_addc_u32 s37, s37, 0
	global_load_dwordx4 v[142:145], v247, s[36:37]
	s_add_u32 s36, s36, 0x4000
	s_addc_u32 s37, s37, 0
	global_load_dwordx4 v[146:149], v247, s[36:37]
	s_add_u32 s36, s36, 0x4000
	s_addc_u32 s37, s37, 0
	global_load_dwordx4 v[150:153], v247, s[36:37]
	s_add_u32 s36, s36, 0x4000
	s_addc_u32 s37, s37, 0
	global_load_dwordx4 v[154:157], v247, s[36:37]
	s_add_u32 s36, s36, 0x4000
	s_addc_u32 s37, s37, 0
	global_load_dwordx4 v[158:161], v247, s[36:37]
	s_add_u32 s36, s36, 0x4000
	s_addc_u32 s37, s37, 0
	global_load_dwordx4 v[162:165], v247, s[36:37]
	s_add_u32 s36, s36, 0x4000
	s_addc_u32 s37, s37, 0
	global_load_dwordx4 v[166:169], v247, s[36:37]
	s_add_u32 s36, s36, 0x4000
	s_addc_u32 s37, s37, 0
	global_load_dwordx4 v[192:195], v247, s[36:37]
	s_add_u32 s36, s36, 0x4000
	s_addc_u32 s37, s37, 0
	global_load_dwordx4 v[196:199], v247, s[36:37]
	s_add_u32 s36, s36, 0x4000
	s_addc_u32 s37, s37, 0
	global_load_dwordx4 v[200:203], v247, s[36:37]
	s_add_u32 s36, s36, 0x4000
	s_addc_u32 s37, s37, 0
	global_load_dwordx4 v[216:219], v247, s[36:37]
	s_add_u32 s36, s36, 0x4000
	s_addc_u32 s37, s37, 0
	global_load_dwordx4 v[220:223], v247, s[36:37]
	s_add_u32 s36, s36, 0x4000
	s_addc_u32 s37, s37, 0
	global_load_dwordx4 v[224:227], v247, s[36:37]
	s_add_u32 s36, s36, 0x4000
	s_addc_u32 s37, s37, 0
	ds_write_b128 v228, v[66:69]
	ds_write_b128 v229, v[70:73]
	ds_write_b128 v230, v[74:77]
	ds_write_b128 v231, v[78:81]
	ds_write_b128 v232, v[114:117]
	ds_write_b128 v233, v[118:121]
	ds_write_b128 v234, v[122:125]
	ds_write_b128 v235, v[126:129]
	ds_write_b128 v228, v[82:85] offset:8192
	ds_write_b128 v229, v[86:89] offset:8192
	ds_write_b128 v230, v[90:93] offset:8192
	ds_write_b128 v231, v[94:97] offset:8192
	ds_write_b128 v232, v[98:101] offset:8192
	ds_write_b128 v233, v[102:105] offset:8192
	ds_write_b128 v234, v[106:109] offset:8192
	ds_write_b128 v235, v[110:113] offset:8192
	global_load_dwordx4 v[66:69], v247, s[36:37]
	s_add_u32 s36, s36, 0x4000
	s_addc_u32 s37, s37, 0
	global_load_dwordx4 v[70:73], v247, s[36:37]
	s_add_u32 s36, s36, 0x4000
	s_addc_u32 s37, s37, 0
	global_load_dwordx4 v[74:77], v247, s[36:37]
	s_add_u32 s36, s36, 0x4000
	s_addc_u32 s37, s37, 0
	global_load_dwordx4 v[78:81], v247, s[36:37]
	s_add_u32 s36, s36, 0x4000
	s_addc_u32 s37, s37, 0
	global_load_dwordx4 v[114:117], v247, s[36:37]
	s_add_u32 s36, s36, 0x4000
	s_addc_u32 s37, s37, 0
	global_load_dwordx4 v[118:121], v247, s[36:37]
	s_add_u32 s36, s36, 0x4000
	s_addc_u32 s37, s37, 0
	global_load_dwordx4 v[122:125], v247, s[36:37]
	s_add_u32 s36, s36, 0x4000
	s_addc_u32 s37, s37, 0
	global_load_dwordx4 v[126:129], v247, s[36:37]
	s_add_u32 s36, s36, 0x4000
	s_addc_u32 s37, s37, 0
	global_load_dwordx4 v[82:85], v247, s[36:37]
	s_add_u32 s36, s36, 0x4000
	s_addc_u32 s37, s37, 0
	global_load_dwordx4 v[86:89], v247, s[36:37]
	s_add_u32 s36, s36, 0x4000
	s_addc_u32 s37, s37, 0
	global_load_dwordx4 v[90:93], v247, s[36:37]
	s_add_u32 s36, s36, 0x4000
	s_addc_u32 s37, s37, 0
	global_load_dwordx4 v[94:97], v247, s[36:37]
	s_add_u32 s36, s36, 0x4000
	s_addc_u32 s37, s37, 0
	global_load_dwordx4 v[98:101], v247, s[36:37]
	s_add_u32 s36, s36, 0x4000
	s_addc_u32 s37, s37, 0
	global_load_dwordx4 v[102:105], v247, s[36:37]
	s_add_u32 s36, s36, 0x4000
	s_addc_u32 s37, s37, 0
	global_load_dwordx4 v[106:109], v247, s[36:37]
	s_add_u32 s36, s36, 0x4000
	s_addc_u32 s37, s37, 0
	global_load_dwordx4 v[110:113], v247, s[36:37]
	s_add_u32 s36, s36, 0x4000
	s_addc_u32 s37, s37, 0
	s_waitcnt lgkmcnt(0)
	ds_read_b128 v[228:231], v210 offset:0
	ds_read_b128 v[238:241], v211 offset:1024
	s_waitcnt vmcnt(31) lgkmcnt(1)
	v_pk_add_f32 v[130:131], v[228:229], v[130:131]
	v_pk_add_f32 v[132:133], v[230:231], v[132:133]
	v_pk_mul_f32 v[232:233], v[130:131], v[130:131]
	v_pk_mul_f32 v[234:235], v[132:133], v[132:133]
	ds_read_b128 v[228:231], v215 offset:2048
	v_add_f32_e32 v236, v232, v233
	v_add_f32_e32 v236, v234, v236
	v_add_f32_e32 v236, v235, v236
	global_store_dwordx4 v247, v[130:133], s[38:39]
	v_cvt_pk_bf16_f32 v232, v130, v131
	v_cvt_pk_bf16_f32 v233, v132, v133
	v_add_f32_dpp v236, v236, v236 quad_perm:[1,0,3,2] row_mask:0xf bank_mask:0xf
	global_store_dwordx2 v248, v[232:233], s[50:51]
	s_add_u32 s38, s38, 0x4000
	s_addc_u32 s39, s39, 0
	v_add_f32_dpp v236, v236, v236 quad_perm:[2,3,0,1] row_mask:0xf bank_mask:0xf
	s_add_u32 s50, s50, 0x2000
	s_addc_u32 s51, s51, 0
	v_add_f32_dpp v236, v236, v236 row_half_mirror row_mask:0xf bank_mask:0xf
	s_nop 1
	v_add_f32_dpp v236, v236, v236 row_mirror row_mask:0xf bank_mask:0xf
	s_mov_b64 exec, s[48:49]
	global_store_dword v249, v236, s[34:35] offset:0
	s_mov_b64 exec, -1
	s_waitcnt vmcnt(33) lgkmcnt(1)
	v_pk_add_f32 v[134:135], v[238:239], v[134:135]
	v_pk_add_f32 v[136:137], v[240:241], v[136:137]
	v_pk_mul_f32 v[242:243], v[134:135], v[134:135]
	v_pk_mul_f32 v[244:245], v[136:137], v[136:137]
	ds_read_b128 v[238:241], v237 offset:3072
	v_add_f32_e32 v246, v242, v243
	v_add_f32_e32 v246, v244, v246
	v_add_f32_e32 v246, v245, v246
	global_store_dwordx4 v247, v[134:137], s[38:39]
	v_cvt_pk_bf16_f32 v242, v134, v135
	v_cvt_pk_bf16_f32 v243, v136, v137
	v_add_f32_dpp v246, v246, v246 quad_perm:[1,0,3,2] row_mask:0xf bank_mask:0xf
	global_store_dwordx2 v248, v[242:243], s[50:51]
	s_add_u32 s38, s38, 0x4000
	s_addc_u32 s39, s39, 0
	v_add_f32_dpp v246, v246, v246 quad_perm:[2,3,0,1] row_mask:0xf bank_mask:0xf
	s_add_u32 s50, s50, 0x2000
	s_addc_u32 s51, s51, 0
	v_add_f32_dpp v246, v246, v246 row_half_mirror row_mask:0xf bank_mask:0xf
	s_nop 1
	v_add_f32_dpp v246, v246, v246 row_mirror row_mask:0xf bank_mask:0xf
	s_mov_b64 exec, s[48:49]
	global_store_dword v249, v246, s[34:35] offset:256
	s_mov_b64 exec, -1
	s_waitcnt vmcnt(35) lgkmcnt(1)
	v_pk_add_f32 v[138:139], v[228:229], v[138:139]
	v_pk_add_f32 v[140:141], v[230:231], v[140:141]
	v_pk_mul_f32 v[232:233], v[138:139], v[138:139]
	v_pk_mul_f32 v[234:235], v[140:141], v[140:141]
	ds_read_b128 v[228:231], v210 offset:4096
	v_add_f32_e32 v236, v232, v233
	v_add_f32_e32 v236, v234, v236
	v_add_f32_e32 v236, v235, v236
	global_store_dwordx4 v247, v[138:141], s[38:39]
	v_cvt_pk_bf16_f32 v232, v138, v139
	v_cvt_pk_bf16_f32 v233, v140, v141
	v_add_f32_dpp v236, v236, v236 quad_perm:[1,0,3,2] row_mask:0xf bank_mask:0xf
	global_store_dwordx2 v248, v[232:233], s[50:51]
	s_add_u32 s38, s38, 0x4000
	s_addc_u32 s39, s39, 0
	v_add_f32_dpp v236, v236, v236 quad_perm:[2,3,0,1] row_mask:0xf bank_mask:0xf
	s_add_u32 s50, s50, 0x2000
	s_addc_u32 s51, s51, 0
	v_add_f32_dpp v236, v236, v236 row_half_mirror row_mask:0xf bank_mask:0xf
	s_nop 1
	v_add_f32_dpp v236, v236, v236 row_mirror row_mask:0xf bank_mask:0xf
	s_mov_b64 exec, s[48:49]
	global_store_dword v249, v236, s[34:35] offset:512
	s_mov_b64 exec, -1
	s_waitcnt vmcnt(37) lgkmcnt(1)
	v_pk_add_f32 v[142:143], v[238:239], v[142:143]
	v_pk_add_f32 v[144:145], v[240:241], v[144:145]
	v_pk_mul_f32 v[242:243], v[142:143], v[142:143]
	v_pk_mul_f32 v[244:245], v[144:145], v[144:145]
	ds_read_b128 v[238:241], v211 offset:5120
	v_add_f32_e32 v246, v242, v243
	v_add_f32_e32 v246, v244, v246
	v_add_f32_e32 v246, v245, v246
	global_store_dwordx4 v247, v[142:145], s[38:39]
	v_cvt_pk_bf16_f32 v242, v142, v143
	v_cvt_pk_bf16_f32 v243, v144, v145
	v_add_f32_dpp v246, v246, v246 quad_perm:[1,0,3,2] row_mask:0xf bank_mask:0xf
	global_store_dwordx2 v248, v[242:243], s[50:51]
	s_add_u32 s38, s38, 0x4000
	s_addc_u32 s39, s39, 0
	v_add_f32_dpp v246, v246, v246 quad_perm:[2,3,0,1] row_mask:0xf bank_mask:0xf
	s_add_u32 s50, s50, 0x2000
	s_addc_u32 s51, s51, 0
	v_add_f32_dpp v246, v246, v246 row_half_mirror row_mask:0xf bank_mask:0xf
	s_nop 1
	v_add_f32_dpp v246, v246, v246 row_mirror row_mask:0xf bank_mask:0xf
	s_mov_b64 exec, s[48:49]
	global_store_dword v249, v246, s[34:35] offset:768
	s_mov_b64 exec, -1
	s_waitcnt vmcnt(39) lgkmcnt(1)
	v_pk_add_f32 v[146:147], v[228:229], v[146:147]
	v_pk_add_f32 v[148:149], v[230:231], v[148:149]
	v_pk_mul_f32 v[232:233], v[146:147], v[146:147]
	v_pk_mul_f32 v[234:235], v[148:149], v[148:149]
	ds_read_b128 v[228:231], v215 offset:6144
	v_add_f32_e32 v236, v232, v233
	v_add_f32_e32 v236, v234, v236
	v_add_f32_e32 v236, v235, v236
	global_store_dwordx4 v247, v[146:149], s[38:39]
	v_cvt_pk_bf16_f32 v232, v146, v147
	v_cvt_pk_bf16_f32 v233, v148, v149
	v_add_f32_dpp v236, v236, v236 quad_perm:[1,0,3,2] row_mask:0xf bank_mask:0xf
	global_store_dwordx2 v248, v[232:233], s[50:51]
	s_add_u32 s38, s38, 0x4000
	s_addc_u32 s39, s39, 0
	v_add_f32_dpp v236, v236, v236 quad_perm:[2,3,0,1] row_mask:0xf bank_mask:0xf
	s_add_u32 s50, s50, 0x2000
	s_addc_u32 s51, s51, 0
	v_add_f32_dpp v236, v236, v236 row_half_mirror row_mask:0xf bank_mask:0xf
	s_nop 1
	v_add_f32_dpp v236, v236, v236 row_mirror row_mask:0xf bank_mask:0xf
	s_mov_b64 exec, s[48:49]
	global_store_dword v249, v236, s[34:35] offset:1024
	s_mov_b64 exec, -1
	s_waitcnt vmcnt(41) lgkmcnt(1)
	v_pk_add_f32 v[150:151], v[238:239], v[150:151]
	v_pk_add_f32 v[152:153], v[240:241], v[152:153]
	v_pk_mul_f32 v[242:243], v[150:151], v[150:151]
	v_pk_mul_f32 v[244:245], v[152:153], v[152:153]
	ds_read_b128 v[238:241], v237 offset:7168
	v_add_f32_e32 v246, v242, v243
	v_add_f32_e32 v246, v244, v246
	v_add_f32_e32 v246, v245, v246
	global_store_dwordx4 v247, v[150:153], s[38:39]
	v_cvt_pk_bf16_f32 v242, v150, v151
	v_cvt_pk_bf16_f32 v243, v152, v153
	v_add_f32_dpp v246, v246, v246 quad_perm:[1,0,3,2] row_mask:0xf bank_mask:0xf
	global_store_dwordx2 v248, v[242:243], s[50:51]
	s_add_u32 s38, s38, 0x4000
	s_addc_u32 s39, s39, 0
	v_add_f32_dpp v246, v246, v246 quad_perm:[2,3,0,1] row_mask:0xf bank_mask:0xf
	s_add_u32 s50, s50, 0x2000
	s_addc_u32 s51, s51, 0
	v_add_f32_dpp v246, v246, v246 row_half_mirror row_mask:0xf bank_mask:0xf
	s_nop 1
	v_add_f32_dpp v246, v246, v246 row_mirror row_mask:0xf bank_mask:0xf
	s_mov_b64 exec, s[48:49]
	global_store_dword v249, v246, s[34:35] offset:1280
	s_mov_b64 exec, -1
	s_waitcnt vmcnt(43) lgkmcnt(1)
	v_pk_add_f32 v[154:155], v[228:229], v[154:155]
	v_pk_add_f32 v[156:157], v[230:231], v[156:157]
	v_pk_mul_f32 v[232:233], v[154:155], v[154:155]
	v_pk_mul_f32 v[234:235], v[156:157], v[156:157]
	ds_read_b128 v[228:231], v210 offset:8192
	v_add_f32_e32 v236, v232, v233
	v_add_f32_e32 v236, v234, v236
	v_add_f32_e32 v236, v235, v236
	global_store_dwordx4 v247, v[154:157], s[38:39]
	v_cvt_pk_bf16_f32 v232, v154, v155
	v_cvt_pk_bf16_f32 v233, v156, v157
	v_add_f32_dpp v236, v236, v236 quad_perm:[1,0,3,2] row_mask:0xf bank_mask:0xf
	global_store_dwordx2 v248, v[232:233], s[50:51]
	s_add_u32 s38, s38, 0x4000
	s_addc_u32 s39, s39, 0
	v_add_f32_dpp v236, v236, v236 quad_perm:[2,3,0,1] row_mask:0xf bank_mask:0xf
	s_add_u32 s50, s50, 0x2000
	s_addc_u32 s51, s51, 0
	v_add_f32_dpp v236, v236, v236 row_half_mirror row_mask:0xf bank_mask:0xf
	s_nop 1
	v_add_f32_dpp v236, v236, v236 row_mirror row_mask:0xf bank_mask:0xf
	s_mov_b64 exec, s[48:49]
	global_store_dword v249, v236, s[34:35] offset:1536
	s_mov_b64 exec, -1
	s_waitcnt vmcnt(45) lgkmcnt(1)
	v_pk_add_f32 v[158:159], v[238:239], v[158:159]
	v_pk_add_f32 v[160:161], v[240:241], v[160:161]
	v_pk_mul_f32 v[242:243], v[158:159], v[158:159]
	v_pk_mul_f32 v[244:245], v[160:161], v[160:161]
	ds_read_b128 v[238:241], v211 offset:9216
	v_add_f32_e32 v246, v242, v243
	v_add_f32_e32 v246, v244, v246
	v_add_f32_e32 v246, v245, v246
	global_store_dwordx4 v247, v[158:161], s[38:39]
	v_cvt_pk_bf16_f32 v242, v158, v159
	v_cvt_pk_bf16_f32 v243, v160, v161
	v_add_f32_dpp v246, v246, v246 quad_perm:[1,0,3,2] row_mask:0xf bank_mask:0xf
	global_store_dwordx2 v248, v[242:243], s[50:51]
	s_add_u32 s38, s38, 0x4000
	s_addc_u32 s39, s39, 0
	v_add_f32_dpp v246, v246, v246 quad_perm:[2,3,0,1] row_mask:0xf bank_mask:0xf
	s_add_u32 s50, s50, 0x2000
	s_addc_u32 s51, s51, 0
	v_add_f32_dpp v246, v246, v246 row_half_mirror row_mask:0xf bank_mask:0xf
	s_nop 1
	v_add_f32_dpp v246, v246, v246 row_mirror row_mask:0xf bank_mask:0xf
	s_mov_b64 exec, s[48:49]
	global_store_dword v249, v246, s[34:35] offset:1792
	s_mov_b64 exec, -1
	s_waitcnt vmcnt(47) lgkmcnt(1)
	v_pk_add_f32 v[162:163], v[228:229], v[162:163]
	v_pk_add_f32 v[164:165], v[230:231], v[164:165]
	v_pk_mul_f32 v[232:233], v[162:163], v[162:163]
	v_pk_mul_f32 v[234:235], v[164:165], v[164:165]
	ds_read_b128 v[228:231], v215 offset:10240
	v_add_f32_e32 v236, v232, v233
	v_add_f32_e32 v236, v234, v236
	v_add_f32_e32 v236, v235, v236
	global_store_dwordx4 v247, v[162:165], s[38:39]
	v_cvt_pk_bf16_f32 v232, v162, v163
	v_cvt_pk_bf16_f32 v233, v164, v165
	v_add_f32_dpp v236, v236, v236 quad_perm:[1,0,3,2] row_mask:0xf bank_mask:0xf
	global_store_dwordx2 v248, v[232:233], s[50:51]
	s_add_u32 s38, s38, 0x4000
	s_addc_u32 s39, s39, 0
	v_add_f32_dpp v236, v236, v236 quad_perm:[2,3,0,1] row_mask:0xf bank_mask:0xf
	s_add_u32 s50, s50, 0x2000
	s_addc_u32 s51, s51, 0
	v_add_f32_dpp v236, v236, v236 row_half_mirror row_mask:0xf bank_mask:0xf
	s_nop 1
	v_add_f32_dpp v236, v236, v236 row_mirror row_mask:0xf bank_mask:0xf
	s_mov_b64 exec, s[48:49]
	global_store_dword v249, v236, s[34:35] offset:2048
	s_mov_b64 exec, -1
	s_waitcnt vmcnt(49) lgkmcnt(1)
	v_pk_add_f32 v[166:167], v[238:239], v[166:167]
	v_pk_add_f32 v[168:169], v[240:241], v[168:169]
	v_pk_mul_f32 v[242:243], v[166:167], v[166:167]
	v_pk_mul_f32 v[244:245], v[168:169], v[168:169]
	ds_read_b128 v[238:241], v237 offset:11264
	v_add_f32_e32 v246, v242, v243
	v_add_f32_e32 v246, v244, v246
	v_add_f32_e32 v246, v245, v246
	global_store_dwordx4 v247, v[166:169], s[38:39]
	v_cvt_pk_bf16_f32 v242, v166, v167
	v_cvt_pk_bf16_f32 v243, v168, v169
	v_add_f32_dpp v246, v246, v246 quad_perm:[1,0,3,2] row_mask:0xf bank_mask:0xf
	global_store_dwordx2 v248, v[242:243], s[50:51]
	s_add_u32 s38, s38, 0x4000
	s_addc_u32 s39, s39, 0
	v_add_f32_dpp v246, v246, v246 quad_perm:[2,3,0,1] row_mask:0xf bank_mask:0xf
	s_add_u32 s50, s50, 0x2000
	s_addc_u32 s51, s51, 0
	v_add_f32_dpp v246, v246, v246 row_half_mirror row_mask:0xf bank_mask:0xf
	s_nop 1
	v_add_f32_dpp v246, v246, v246 row_mirror row_mask:0xf bank_mask:0xf
	s_mov_b64 exec, s[48:49]
	global_store_dword v249, v246, s[34:35] offset:2304
	s_mov_b64 exec, -1
	s_waitcnt vmcnt(51) lgkmcnt(1)
	v_pk_add_f32 v[192:193], v[228:229], v[192:193]
	v_pk_add_f32 v[194:195], v[230:231], v[194:195]
	v_pk_mul_f32 v[232:233], v[192:193], v[192:193]
	v_pk_mul_f32 v[234:235], v[194:195], v[194:195]
	ds_read_b128 v[228:231], v210 offset:12288
	v_add_f32_e32 v236, v232, v233
	v_add_f32_e32 v236, v234, v236
	v_add_f32_e32 v236, v235, v236
	global_store_dwordx4 v247, v[192:195], s[38:39]
	v_cvt_pk_bf16_f32 v232, v192, v193
	v_cvt_pk_bf16_f32 v233, v194, v195
	v_add_f32_dpp v236, v236, v236 quad_perm:[1,0,3,2] row_mask:0xf bank_mask:0xf
	global_store_dwordx2 v248, v[232:233], s[50:51]
	s_add_u32 s38, s38, 0x4000
	s_addc_u32 s39, s39, 0
	v_add_f32_dpp v236, v236, v236 quad_perm:[2,3,0,1] row_mask:0xf bank_mask:0xf
	s_add_u32 s50, s50, 0x2000
	s_addc_u32 s51, s51, 0
	v_add_f32_dpp v236, v236, v236 row_half_mirror row_mask:0xf bank_mask:0xf
	s_nop 1
	v_add_f32_dpp v236, v236, v236 row_mirror row_mask:0xf bank_mask:0xf
	s_mov_b64 exec, s[48:49]
	global_store_dword v249, v236, s[34:35] offset:2560
	s_mov_b64 exec, -1
	s_waitcnt vmcnt(53) lgkmcnt(1)
	v_pk_add_f32 v[196:197], v[238:239], v[196:197]
	v_pk_add_f32 v[198:199], v[240:241], v[198:199]
	v_pk_mul_f32 v[242:243], v[196:197], v[196:197]
	v_pk_mul_f32 v[244:245], v[198:199], v[198:199]
	ds_read_b128 v[238:241], v211 offset:13312
	v_add_f32_e32 v246, v242, v243
	v_add_f32_e32 v246, v244, v246
	v_add_f32_e32 v246, v245, v246
	global_store_dwordx4 v247, v[196:199], s[38:39]
	v_cvt_pk_bf16_f32 v242, v196, v197
	v_cvt_pk_bf16_f32 v243, v198, v199
	v_add_f32_dpp v246, v246, v246 quad_perm:[1,0,3,2] row_mask:0xf bank_mask:0xf
	global_store_dwordx2 v248, v[242:243], s[50:51]
	s_add_u32 s38, s38, 0x4000
	s_addc_u32 s39, s39, 0
	v_add_f32_dpp v246, v246, v246 quad_perm:[2,3,0,1] row_mask:0xf bank_mask:0xf
	s_add_u32 s50, s50, 0x2000
	s_addc_u32 s51, s51, 0
	v_add_f32_dpp v246, v246, v246 row_half_mirror row_mask:0xf bank_mask:0xf
	s_nop 1
	v_add_f32_dpp v246, v246, v246 row_mirror row_mask:0xf bank_mask:0xf
	s_mov_b64 exec, s[48:49]
	global_store_dword v249, v246, s[34:35] offset:2816
	s_mov_b64 exec, -1
	s_waitcnt vmcnt(55) lgkmcnt(1)
	v_pk_add_f32 v[200:201], v[228:229], v[200:201]
	v_pk_add_f32 v[202:203], v[230:231], v[202:203]
	v_pk_mul_f32 v[232:233], v[200:201], v[200:201]
	v_pk_mul_f32 v[234:235], v[202:203], v[202:203]
	ds_read_b128 v[228:231], v215 offset:14336
	v_add_f32_e32 v236, v232, v233
	v_add_f32_e32 v236, v234, v236
	v_add_f32_e32 v236, v235, v236
	global_store_dwordx4 v247, v[200:203], s[38:39]
	v_cvt_pk_bf16_f32 v232, v200, v201
	v_cvt_pk_bf16_f32 v233, v202, v203
	v_add_f32_dpp v236, v236, v236 quad_perm:[1,0,3,2] row_mask:0xf bank_mask:0xf
	global_store_dwordx2 v248, v[232:233], s[50:51]
	s_add_u32 s38, s38, 0x4000
	s_addc_u32 s39, s39, 0
	v_add_f32_dpp v236, v236, v236 quad_perm:[2,3,0,1] row_mask:0xf bank_mask:0xf
	s_add_u32 s50, s50, 0x2000
	s_addc_u32 s51, s51, 0
	v_add_f32_dpp v236, v236, v236 row_half_mirror row_mask:0xf bank_mask:0xf
	s_nop 1
	v_add_f32_dpp v236, v236, v236 row_mirror row_mask:0xf bank_mask:0xf
	s_mov_b64 exec, s[48:49]
	global_store_dword v249, v236, s[34:35] offset:3072
	s_mov_b64 exec, -1
	s_waitcnt vmcnt(57) lgkmcnt(1)
	v_pk_add_f32 v[216:217], v[238:239], v[216:217]
	v_pk_add_f32 v[218:219], v[240:241], v[218:219]
	v_pk_mul_f32 v[242:243], v[216:217], v[216:217]
	v_pk_mul_f32 v[244:245], v[218:219], v[218:219]
	ds_read_b128 v[238:241], v237 offset:15360
	v_add_f32_e32 v246, v242, v243
	v_add_f32_e32 v246, v244, v246
	v_add_f32_e32 v246, v245, v246
	global_store_dwordx4 v247, v[216:219], s[38:39]
	v_cvt_pk_bf16_f32 v242, v216, v217
	v_cvt_pk_bf16_f32 v243, v218, v219
	v_add_f32_dpp v246, v246, v246 quad_perm:[1,0,3,2] row_mask:0xf bank_mask:0xf
	global_store_dwordx2 v248, v[242:243], s[50:51]
	s_add_u32 s38, s38, 0x4000
	s_addc_u32 s39, s39, 0
	v_add_f32_dpp v246, v246, v246 quad_perm:[2,3,0,1] row_mask:0xf bank_mask:0xf
	s_add_u32 s50, s50, 0x2000
	s_addc_u32 s51, s51, 0
	v_add_f32_dpp v246, v246, v246 row_half_mirror row_mask:0xf bank_mask:0xf
	s_nop 1
	v_add_f32_dpp v246, v246, v246 row_mirror row_mask:0xf bank_mask:0xf
	s_mov_b64 exec, s[48:49]
	global_store_dword v249, v246, s[34:35] offset:3328
	s_mov_b64 exec, -1
	s_waitcnt vmcnt(59) lgkmcnt(1)
	v_pk_add_f32 v[220:221], v[228:229], v[220:221]
	v_pk_add_f32 v[222:223], v[230:231], v[222:223]
	v_pk_mul_f32 v[232:233], v[220:221], v[220:221]
	v_pk_mul_f32 v[234:235], v[222:223], v[222:223]
	v_add_f32_e32 v236, v232, v233
	v_add_f32_e32 v236, v234, v236
	v_add_f32_e32 v236, v235, v236
	global_store_dwordx4 v247, v[220:223], s[38:39]
	v_cvt_pk_bf16_f32 v232, v220, v221
	v_cvt_pk_bf16_f32 v233, v222, v223
	v_add_f32_dpp v236, v236, v236 quad_perm:[1,0,3,2] row_mask:0xf bank_mask:0xf
	global_store_dwordx2 v248, v[232:233], s[50:51]
	s_add_u32 s38, s38, 0x4000
	s_addc_u32 s39, s39, 0
	v_add_f32_dpp v236, v236, v236 quad_perm:[2,3,0,1] row_mask:0xf bank_mask:0xf
	s_add_u32 s50, s50, 0x2000
	s_addc_u32 s51, s51, 0
	v_add_f32_dpp v236, v236, v236 row_half_mirror row_mask:0xf bank_mask:0xf
	s_nop 1
	v_add_f32_dpp v236, v236, v236 row_mirror row_mask:0xf bank_mask:0xf
	s_mov_b64 exec, s[48:49]
	global_store_dword v249, v236, s[34:35] offset:3584
	s_mov_b64 exec, -1
	s_waitcnt vmcnt(61) lgkmcnt(0)
	v_pk_add_f32 v[224:225], v[238:239], v[224:225]
	v_pk_add_f32 v[226:227], v[240:241], v[226:227]
	v_pk_mul_f32 v[242:243], v[224:225], v[224:225]
	v_pk_mul_f32 v[244:245], v[226:227], v[226:227]
	v_add_f32_e32 v246, v242, v243
	v_add_f32_e32 v246, v244, v246
	v_add_f32_e32 v246, v245, v246
	global_store_dwordx4 v247, v[224:227], s[38:39]
	v_cvt_pk_bf16_f32 v242, v224, v225
	v_cvt_pk_bf16_f32 v243, v226, v227
	v_add_f32_dpp v246, v246, v246 quad_perm:[1,0,3,2] row_mask:0xf bank_mask:0xf
	global_store_dwordx2 v248, v[242:243], s[50:51]
	s_add_u32 s38, s38, 0x4000
	s_addc_u32 s39, s39, 0
	v_add_f32_dpp v246, v246, v246 quad_perm:[2,3,0,1] row_mask:0xf bank_mask:0xf
	s_add_u32 s50, s50, 0x2000
	s_addc_u32 s51, s51, 0
	v_add_f32_dpp v246, v246, v246 row_half_mirror row_mask:0xf bank_mask:0xf
	s_nop 1
	v_add_f32_dpp v246, v246, v246 row_mirror row_mask:0xf bank_mask:0xf
	s_mov_b64 exec, s[48:49]
	global_store_dword v249, v246, s[34:35] offset:3840
	s_mov_b64 exec, -1
	s_add_u32 s34, s34, 0x1000
	s_addc_u32 s35, s35, 0
	v_and_b32_e32 v238, 15, v170
	v_xor_b32_e32 v238, v238, v171
	v_lshl_add_u32 v239, v170, 8, s40
	v_xor_b32_e32 v228, 0, v238
	v_lshl_add_u32 v228, v228, 4, v239
	v_xor_b32_e32 v229, 2, v238
	v_lshl_add_u32 v229, v229, 4, v239
	v_xor_b32_e32 v230, 4, v238
	v_lshl_add_u32 v230, v230, 4, v239
	v_xor_b32_e32 v231, 6, v238
	v_lshl_add_u32 v231, v231, 4, v239
	v_xor_b32_e32 v232, 8, v238
	v_lshl_add_u32 v232, v232, 4, v239
	v_xor_b32_e32 v233, 10, v238
	v_lshl_add_u32 v233, v233, 4, v239
	v_xor_b32_e32 v234, 12, v238
	v_lshl_add_u32 v234, v234, 4, v239
	v_xor_b32_e32 v235, 14, v238
	v_lshl_add_u32 v235, v235, 4, v239
	ds_write_b128 v228, v[18:21]
	ds_write_b128 v229, v[22:25]
	ds_write_b128 v230, v[26:29]
	ds_write_b128 v231, v[30:33]
	ds_write_b128 v232, v[50:53]
	ds_write_b128 v233, v[54:57]
	ds_write_b128 v234, v[58:61]
	ds_write_b128 v235, v[62:65]
	ds_write_b128 v228, v[2:5] offset:8192
	ds_write_b128 v229, v[6:9] offset:8192
	ds_write_b128 v230, v[10:13] offset:8192
	ds_write_b128 v231, v[14:17] offset:8192
	ds_write_b128 v232, v[34:37] offset:8192
	ds_write_b128 v233, v[38:41] offset:8192
	ds_write_b128 v234, v[42:45] offset:8192
	ds_write_b128 v235, v[46:49] offset:8192
	s_waitcnt lgkmcnt(0)
	ds_read_b128 v[228:231], v210 offset:0
	ds_read_b128 v[238:241], v211 offset:1024
	s_waitcnt vmcnt(63) lgkmcnt(1)
	v_pk_add_f32 v[66:67], v[228:229], v[66:67]
	v_pk_add_f32 v[68:69], v[230:231], v[68:69]
	v_pk_mul_f32 v[232:233], v[66:67], v[66:67]
	v_pk_mul_f32 v[234:235], v[68:69], v[68:69]
	ds_read_b128 v[228:231], v215 offset:2048
	v_add_f32_e32 v236, v232, v233
	v_add_f32_e32 v236, v234, v236
	v_add_f32_e32 v236, v235, v236
	global_store_dwordx4 v247, v[66:69], s[38:39]
	v_cvt_pk_bf16_f32 v232, v66, v67
	v_cvt_pk_bf16_f32 v233, v68, v69
	v_add_f32_dpp v236, v236, v236 quad_perm:[1,0,3,2] row_mask:0xf bank_mask:0xf
	global_store_dwordx2 v248, v[232:233], s[50:51]
	s_add_u32 s38, s38, 0x4000
	s_addc_u32 s39, s39, 0
	v_add_f32_dpp v236, v236, v236 quad_perm:[2,3,0,1] row_mask:0xf bank_mask:0xf
	s_add_u32 s50, s50, 0x2000
	s_addc_u32 s51, s51, 0
	v_add_f32_dpp v236, v236, v236 row_half_mirror row_mask:0xf bank_mask:0xf
	s_nop 1
	v_add_f32_dpp v236, v236, v236 row_mirror row_mask:0xf bank_mask:0xf
	s_mov_b64 exec, s[48:49]
	global_store_dword v249, v236, s[34:35] offset:0
	s_mov_b64 exec, -1
	s_waitcnt vmcnt(63) lgkmcnt(1)
	v_pk_add_f32 v[70:71], v[238:239], v[70:71]
	v_pk_add_f32 v[72:73], v[240:241], v[72:73]
	v_pk_mul_f32 v[242:243], v[70:71], v[70:71]
	v_pk_mul_f32 v[244:245], v[72:73], v[72:73]
	ds_read_b128 v[238:241], v237 offset:3072
	v_add_f32_e32 v246, v242, v243
	v_add_f32_e32 v246, v244, v246
	v_add_f32_e32 v246, v245, v246
	global_store_dwordx4 v247, v[70:73], s[38:39]
	v_cvt_pk_bf16_f32 v242, v70, v71
	v_cvt_pk_bf16_f32 v243, v72, v73
	v_add_f32_dpp v246, v246, v246 quad_perm:[1,0,3,2] row_mask:0xf bank_mask:0xf
	global_store_dwordx2 v248, v[242:243], s[50:51]
	s_add_u32 s38, s38, 0x4000
	s_addc_u32 s39, s39, 0
	v_add_f32_dpp v246, v246, v246 quad_perm:[2,3,0,1] row_mask:0xf bank_mask:0xf
	s_add_u32 s50, s50, 0x2000
	s_addc_u32 s51, s51, 0
	v_add_f32_dpp v246, v246, v246 row_half_mirror row_mask:0xf bank_mask:0xf
	s_nop 1
	v_add_f32_dpp v246, v246, v246 row_mirror row_mask:0xf bank_mask:0xf
	s_mov_b64 exec, s[48:49]
	global_store_dword v249, v246, s[34:35] offset:256
	s_mov_b64 exec, -1
	s_waitcnt vmcnt(63) lgkmcnt(1)
	v_pk_add_f32 v[74:75], v[228:229], v[74:75]
	v_pk_add_f32 v[76:77], v[230:231], v[76:77]
	v_pk_mul_f32 v[232:233], v[74:75], v[74:75]
	v_pk_mul_f32 v[234:235], v[76:77], v[76:77]
	ds_read_b128 v[228:231], v210 offset:4096
	v_add_f32_e32 v236, v232, v233
	v_add_f32_e32 v236, v234, v236
	v_add_f32_e32 v236, v235, v236
	global_store_dwordx4 v247, v[74:77], s[38:39]
	v_cvt_pk_bf16_f32 v232, v74, v75
	v_cvt_pk_bf16_f32 v233, v76, v77
	v_add_f32_dpp v236, v236, v236 quad_perm:[1,0,3,2] row_mask:0xf bank_mask:0xf
	global_store_dwordx2 v248, v[232:233], s[50:51]
	s_add_u32 s38, s38, 0x4000
	s_addc_u32 s39, s39, 0
	v_add_f32_dpp v236, v236, v236 quad_perm:[2,3,0,1] row_mask:0xf bank_mask:0xf
	s_add_u32 s50, s50, 0x2000
	s_addc_u32 s51, s51, 0
	v_add_f32_dpp v236, v236, v236 row_half_mirror row_mask:0xf bank_mask:0xf
	s_nop 1
	v_add_f32_dpp v236, v236, v236 row_mirror row_mask:0xf bank_mask:0xf
	s_mov_b64 exec, s[48:49]
	global_store_dword v249, v236, s[34:35] offset:512
	s_mov_b64 exec, -1
	s_waitcnt vmcnt(63) lgkmcnt(1)
	v_pk_add_f32 v[78:79], v[238:239], v[78:79]
	v_pk_add_f32 v[80:81], v[240:241], v[80:81]
	v_pk_mul_f32 v[242:243], v[78:79], v[78:79]
	v_pk_mul_f32 v[244:245], v[80:81], v[80:81]
	ds_read_b128 v[238:241], v211 offset:5120
	v_add_f32_e32 v246, v242, v243
	v_add_f32_e32 v246, v244, v246
	v_add_f32_e32 v246, v245, v246
	global_store_dwordx4 v247, v[78:81], s[38:39]
	v_cvt_pk_bf16_f32 v242, v78, v79
	v_cvt_pk_bf16_f32 v243, v80, v81
	v_add_f32_dpp v246, v246, v246 quad_perm:[1,0,3,2] row_mask:0xf bank_mask:0xf
	global_store_dwordx2 v248, v[242:243], s[50:51]
	s_add_u32 s38, s38, 0x4000
	s_addc_u32 s39, s39, 0
	v_add_f32_dpp v246, v246, v246 quad_perm:[2,3,0,1] row_mask:0xf bank_mask:0xf
	s_add_u32 s50, s50, 0x2000
	s_addc_u32 s51, s51, 0
	v_add_f32_dpp v246, v246, v246 row_half_mirror row_mask:0xf bank_mask:0xf
	s_nop 1
	v_add_f32_dpp v246, v246, v246 row_mirror row_mask:0xf bank_mask:0xf
	s_mov_b64 exec, s[48:49]
	global_store_dword v249, v246, s[34:35] offset:768
	s_mov_b64 exec, -1
	s_waitcnt vmcnt(63) lgkmcnt(1)
	v_pk_add_f32 v[114:115], v[228:229], v[114:115]
	v_pk_add_f32 v[116:117], v[230:231], v[116:117]
	v_pk_mul_f32 v[232:233], v[114:115], v[114:115]
	v_pk_mul_f32 v[234:235], v[116:117], v[116:117]
	ds_read_b128 v[228:231], v215 offset:6144
	v_add_f32_e32 v236, v232, v233
	v_add_f32_e32 v236, v234, v236
	v_add_f32_e32 v236, v235, v236
	global_store_dwordx4 v247, v[114:117], s[38:39]
	v_cvt_pk_bf16_f32 v232, v114, v115
	v_cvt_pk_bf16_f32 v233, v116, v117
	v_add_f32_dpp v236, v236, v236 quad_perm:[1,0,3,2] row_mask:0xf bank_mask:0xf
	global_store_dwordx2 v248, v[232:233], s[50:51]
	s_add_u32 s38, s38, 0x4000
	s_addc_u32 s39, s39, 0
	v_add_f32_dpp v236, v236, v236 quad_perm:[2,3,0,1] row_mask:0xf bank_mask:0xf
	s_add_u32 s50, s50, 0x2000
	s_addc_u32 s51, s51, 0
	v_add_f32_dpp v236, v236, v236 row_half_mirror row_mask:0xf bank_mask:0xf
	s_nop 1
	v_add_f32_dpp v236, v236, v236 row_mirror row_mask:0xf bank_mask:0xf
	s_mov_b64 exec, s[48:49]
	global_store_dword v249, v236, s[34:35] offset:1024
	s_mov_b64 exec, -1
	s_waitcnt vmcnt(63) lgkmcnt(1)
	v_pk_add_f32 v[118:119], v[238:239], v[118:119]
	v_pk_add_f32 v[120:121], v[240:241], v[120:121]
	v_pk_mul_f32 v[242:243], v[118:119], v[118:119]
	v_pk_mul_f32 v[244:245], v[120:121], v[120:121]
	ds_read_b128 v[238:241], v237 offset:7168
	v_add_f32_e32 v246, v242, v243
	v_add_f32_e32 v246, v244, v246
	v_add_f32_e32 v246, v245, v246
	global_store_dwordx4 v247, v[118:121], s[38:39]
	v_cvt_pk_bf16_f32 v242, v118, v119
	v_cvt_pk_bf16_f32 v243, v120, v121
	v_add_f32_dpp v246, v246, v246 quad_perm:[1,0,3,2] row_mask:0xf bank_mask:0xf
	global_store_dwordx2 v248, v[242:243], s[50:51]
	s_add_u32 s38, s38, 0x4000
	s_addc_u32 s39, s39, 0
	v_add_f32_dpp v246, v246, v246 quad_perm:[2,3,0,1] row_mask:0xf bank_mask:0xf
	s_add_u32 s50, s50, 0x2000
	s_addc_u32 s51, s51, 0
	v_add_f32_dpp v246, v246, v246 row_half_mirror row_mask:0xf bank_mask:0xf
	s_nop 1
	v_add_f32_dpp v246, v246, v246 row_mirror row_mask:0xf bank_mask:0xf
	s_mov_b64 exec, s[48:49]
	global_store_dword v249, v246, s[34:35] offset:1280
	s_mov_b64 exec, -1
	s_waitcnt vmcnt(63) lgkmcnt(1)
	v_pk_add_f32 v[122:123], v[228:229], v[122:123]
	v_pk_add_f32 v[124:125], v[230:231], v[124:125]
	v_pk_mul_f32 v[232:233], v[122:123], v[122:123]
	v_pk_mul_f32 v[234:235], v[124:125], v[124:125]
	ds_read_b128 v[228:231], v210 offset:8192
	v_add_f32_e32 v236, v232, v233
	v_add_f32_e32 v236, v234, v236
	v_add_f32_e32 v236, v235, v236
	global_store_dwordx4 v247, v[122:125], s[38:39]
	v_cvt_pk_bf16_f32 v232, v122, v123
	v_cvt_pk_bf16_f32 v233, v124, v125
	v_add_f32_dpp v236, v236, v236 quad_perm:[1,0,3,2] row_mask:0xf bank_mask:0xf
	global_store_dwordx2 v248, v[232:233], s[50:51]
	s_add_u32 s38, s38, 0x4000
	s_addc_u32 s39, s39, 0
	v_add_f32_dpp v236, v236, v236 quad_perm:[2,3,0,1] row_mask:0xf bank_mask:0xf
	s_add_u32 s50, s50, 0x2000
	s_addc_u32 s51, s51, 0
	v_add_f32_dpp v236, v236, v236 row_half_mirror row_mask:0xf bank_mask:0xf
	s_nop 1
	v_add_f32_dpp v236, v236, v236 row_mirror row_mask:0xf bank_mask:0xf
	s_mov_b64 exec, s[48:49]
	global_store_dword v249, v236, s[34:35] offset:1536
	s_mov_b64 exec, -1
	s_waitcnt vmcnt(63) lgkmcnt(1)
	v_pk_add_f32 v[126:127], v[238:239], v[126:127]
	v_pk_add_f32 v[128:129], v[240:241], v[128:129]
	v_pk_mul_f32 v[242:243], v[126:127], v[126:127]
	v_pk_mul_f32 v[244:245], v[128:129], v[128:129]
	ds_read_b128 v[238:241], v211 offset:9216
	v_add_f32_e32 v246, v242, v243
	v_add_f32_e32 v246, v244, v246
	v_add_f32_e32 v246, v245, v246
	global_store_dwordx4 v247, v[126:129], s[38:39]
	v_cvt_pk_bf16_f32 v242, v126, v127
	v_cvt_pk_bf16_f32 v243, v128, v129
	v_add_f32_dpp v246, v246, v246 quad_perm:[1,0,3,2] row_mask:0xf bank_mask:0xf
	global_store_dwordx2 v248, v[242:243], s[50:51]
	s_add_u32 s38, s38, 0x4000
	s_addc_u32 s39, s39, 0
	v_add_f32_dpp v246, v246, v246 quad_perm:[2,3,0,1] row_mask:0xf bank_mask:0xf
	s_add_u32 s50, s50, 0x2000
	s_addc_u32 s51, s51, 0
	v_add_f32_dpp v246, v246, v246 row_half_mirror row_mask:0xf bank_mask:0xf
	s_nop 1
	v_add_f32_dpp v246, v246, v246 row_mirror row_mask:0xf bank_mask:0xf
	s_mov_b64 exec, s[48:49]
	global_store_dword v249, v246, s[34:35] offset:1792
	s_mov_b64 exec, -1
	s_waitcnt vmcnt(63) lgkmcnt(1)
	v_pk_add_f32 v[82:83], v[228:229], v[82:83]
	v_pk_add_f32 v[84:85], v[230:231], v[84:85]
	v_pk_mul_f32 v[232:233], v[82:83], v[82:83]
	v_pk_mul_f32 v[234:235], v[84:85], v[84:85]
	ds_read_b128 v[228:231], v215 offset:10240
	v_add_f32_e32 v236, v232, v233
	v_add_f32_e32 v236, v234, v236
	v_add_f32_e32 v236, v235, v236
	global_store_dwordx4 v247, v[82:85], s[38:39]
	v_cvt_pk_bf16_f32 v232, v82, v83
	v_cvt_pk_bf16_f32 v233, v84, v85
	v_add_f32_dpp v236, v236, v236 quad_perm:[1,0,3,2] row_mask:0xf bank_mask:0xf
	global_store_dwordx2 v248, v[232:233], s[50:51]
	s_add_u32 s38, s38, 0x4000
	s_addc_u32 s39, s39, 0
	v_add_f32_dpp v236, v236, v236 quad_perm:[2,3,0,1] row_mask:0xf bank_mask:0xf
	s_add_u32 s50, s50, 0x2000
	s_addc_u32 s51, s51, 0
	v_add_f32_dpp v236, v236, v236 row_half_mirror row_mask:0xf bank_mask:0xf
	s_nop 1
	v_add_f32_dpp v236, v236, v236 row_mirror row_mask:0xf bank_mask:0xf
	s_mov_b64 exec, s[48:49]
	global_store_dword v249, v236, s[34:35] offset:2048
	s_mov_b64 exec, -1
	s_waitcnt vmcnt(63) lgkmcnt(1)
	v_pk_add_f32 v[86:87], v[238:239], v[86:87]
	v_pk_add_f32 v[88:89], v[240:241], v[88:89]
	v_pk_mul_f32 v[242:243], v[86:87], v[86:87]
	v_pk_mul_f32 v[244:245], v[88:89], v[88:89]
	ds_read_b128 v[238:241], v237 offset:11264
	v_add_f32_e32 v246, v242, v243
	v_add_f32_e32 v246, v244, v246
	v_add_f32_e32 v246, v245, v246
	global_store_dwordx4 v247, v[86:89], s[38:39]
	v_cvt_pk_bf16_f32 v242, v86, v87
	v_cvt_pk_bf16_f32 v243, v88, v89
	v_add_f32_dpp v246, v246, v246 quad_perm:[1,0,3,2] row_mask:0xf bank_mask:0xf
	global_store_dwordx2 v248, v[242:243], s[50:51]
	s_add_u32 s38, s38, 0x4000
	s_addc_u32 s39, s39, 0
	v_add_f32_dpp v246, v246, v246 quad_perm:[2,3,0,1] row_mask:0xf bank_mask:0xf
	s_add_u32 s50, s50, 0x2000
	s_addc_u32 s51, s51, 0
	v_add_f32_dpp v246, v246, v246 row_half_mirror row_mask:0xf bank_mask:0xf
	s_nop 1
	v_add_f32_dpp v246, v246, v246 row_mirror row_mask:0xf bank_mask:0xf
	s_mov_b64 exec, s[48:49]
	global_store_dword v249, v246, s[34:35] offset:2304
	s_mov_b64 exec, -1
	s_waitcnt vmcnt(63) lgkmcnt(1)
	v_pk_add_f32 v[90:91], v[228:229], v[90:91]
	v_pk_add_f32 v[92:93], v[230:231], v[92:93]
	v_pk_mul_f32 v[232:233], v[90:91], v[90:91]
	v_pk_mul_f32 v[234:235], v[92:93], v[92:93]
	ds_read_b128 v[228:231], v210 offset:12288
	v_add_f32_e32 v236, v232, v233
	v_add_f32_e32 v236, v234, v236
	v_add_f32_e32 v236, v235, v236
	global_store_dwordx4 v247, v[90:93], s[38:39]
	v_cvt_pk_bf16_f32 v232, v90, v91
	v_cvt_pk_bf16_f32 v233, v92, v93
	v_add_f32_dpp v236, v236, v236 quad_perm:[1,0,3,2] row_mask:0xf bank_mask:0xf
	global_store_dwordx2 v248, v[232:233], s[50:51]
	s_add_u32 s38, s38, 0x4000
	s_addc_u32 s39, s39, 0
	v_add_f32_dpp v236, v236, v236 quad_perm:[2,3,0,1] row_mask:0xf bank_mask:0xf
	s_add_u32 s50, s50, 0x2000
	s_addc_u32 s51, s51, 0
	v_add_f32_dpp v236, v236, v236 row_half_mirror row_mask:0xf bank_mask:0xf
	s_nop 1
	v_add_f32_dpp v236, v236, v236 row_mirror row_mask:0xf bank_mask:0xf
	s_mov_b64 exec, s[48:49]
	global_store_dword v249, v236, s[34:35] offset:2560
	s_mov_b64 exec, -1
	s_waitcnt vmcnt(63) lgkmcnt(1)
	v_pk_add_f32 v[94:95], v[238:239], v[94:95]
	v_pk_add_f32 v[96:97], v[240:241], v[96:97]
	v_pk_mul_f32 v[242:243], v[94:95], v[94:95]
	v_pk_mul_f32 v[244:245], v[96:97], v[96:97]
	ds_read_b128 v[238:241], v211 offset:13312
	v_add_f32_e32 v246, v242, v243
	v_add_f32_e32 v246, v244, v246
	v_add_f32_e32 v246, v245, v246
	global_store_dwordx4 v247, v[94:97], s[38:39]
	v_cvt_pk_bf16_f32 v242, v94, v95
	v_cvt_pk_bf16_f32 v243, v96, v97
	v_add_f32_dpp v246, v246, v246 quad_perm:[1,0,3,2] row_mask:0xf bank_mask:0xf
	global_store_dwordx2 v248, v[242:243], s[50:51]
	s_add_u32 s38, s38, 0x4000
	s_addc_u32 s39, s39, 0
	v_add_f32_dpp v246, v246, v246 quad_perm:[2,3,0,1] row_mask:0xf bank_mask:0xf
	s_add_u32 s50, s50, 0x2000
	s_addc_u32 s51, s51, 0
	v_add_f32_dpp v246, v246, v246 row_half_mirror row_mask:0xf bank_mask:0xf
	s_nop 1
	v_add_f32_dpp v246, v246, v246 row_mirror row_mask:0xf bank_mask:0xf
	s_mov_b64 exec, s[48:49]
	global_store_dword v249, v246, s[34:35] offset:2816
	s_mov_b64 exec, -1
	s_waitcnt vmcnt(63) lgkmcnt(1)
	v_pk_add_f32 v[98:99], v[228:229], v[98:99]
	v_pk_add_f32 v[100:101], v[230:231], v[100:101]
	v_pk_mul_f32 v[232:233], v[98:99], v[98:99]
	v_pk_mul_f32 v[234:235], v[100:101], v[100:101]
	ds_read_b128 v[228:231], v215 offset:14336
	v_add_f32_e32 v236, v232, v233
	v_add_f32_e32 v236, v234, v236
	v_add_f32_e32 v236, v235, v236
	global_store_dwordx4 v247, v[98:101], s[38:39]
	v_cvt_pk_bf16_f32 v232, v98, v99
	v_cvt_pk_bf16_f32 v233, v100, v101
	v_add_f32_dpp v236, v236, v236 quad_perm:[1,0,3,2] row_mask:0xf bank_mask:0xf
	global_store_dwordx2 v248, v[232:233], s[50:51]
	s_add_u32 s38, s38, 0x4000
	s_addc_u32 s39, s39, 0
	v_add_f32_dpp v236, v236, v236 quad_perm:[2,3,0,1] row_mask:0xf bank_mask:0xf
	s_add_u32 s50, s50, 0x2000
	s_addc_u32 s51, s51, 0
	v_add_f32_dpp v236, v236, v236 row_half_mirror row_mask:0xf bank_mask:0xf
	s_nop 1
	v_add_f32_dpp v236, v236, v236 row_mirror row_mask:0xf bank_mask:0xf
	s_mov_b64 exec, s[48:49]
	global_store_dword v249, v236, s[34:35] offset:3072
	s_mov_b64 exec, -1
	s_waitcnt vmcnt(63) lgkmcnt(1)
	v_pk_add_f32 v[102:103], v[238:239], v[102:103]
	v_pk_add_f32 v[104:105], v[240:241], v[104:105]
	v_pk_mul_f32 v[242:243], v[102:103], v[102:103]
	v_pk_mul_f32 v[244:245], v[104:105], v[104:105]
	ds_read_b128 v[238:241], v237 offset:15360
	v_add_f32_e32 v246, v242, v243
	v_add_f32_e32 v246, v244, v246
	v_add_f32_e32 v246, v245, v246
	global_store_dwordx4 v247, v[102:105], s[38:39]
	v_cvt_pk_bf16_f32 v242, v102, v103
	v_cvt_pk_bf16_f32 v243, v104, v105
	v_add_f32_dpp v246, v246, v246 quad_perm:[1,0,3,2] row_mask:0xf bank_mask:0xf
	global_store_dwordx2 v248, v[242:243], s[50:51]
	s_add_u32 s38, s38, 0x4000
	s_addc_u32 s39, s39, 0
	v_add_f32_dpp v246, v246, v246 quad_perm:[2,3,0,1] row_mask:0xf bank_mask:0xf
	s_add_u32 s50, s50, 0x2000
	s_addc_u32 s51, s51, 0
	v_add_f32_dpp v246, v246, v246 row_half_mirror row_mask:0xf bank_mask:0xf
	s_nop 1
	v_add_f32_dpp v246, v246, v246 row_mirror row_mask:0xf bank_mask:0xf
	s_mov_b64 exec, s[48:49]
	global_store_dword v249, v246, s[34:35] offset:3328
	s_mov_b64 exec, -1
	s_waitcnt vmcnt(63) lgkmcnt(1)
	v_pk_add_f32 v[106:107], v[228:229], v[106:107]
	v_pk_add_f32 v[108:109], v[230:231], v[108:109]
	v_pk_mul_f32 v[232:233], v[106:107], v[106:107]
	v_pk_mul_f32 v[234:235], v[108:109], v[108:109]
	v_add_f32_e32 v236, v232, v233
	v_add_f32_e32 v236, v234, v236
	v_add_f32_e32 v236, v235, v236
	global_store_dwordx4 v247, v[106:109], s[38:39]
	v_cvt_pk_bf16_f32 v232, v106, v107
	v_cvt_pk_bf16_f32 v233, v108, v109
	v_add_f32_dpp v236, v236, v236 quad_perm:[1,0,3,2] row_mask:0xf bank_mask:0xf
	global_store_dwordx2 v248, v[232:233], s[50:51]
	s_add_u32 s38, s38, 0x4000
	s_addc_u32 s39, s39, 0
	v_add_f32_dpp v236, v236, v236 quad_perm:[2,3,0,1] row_mask:0xf bank_mask:0xf
	s_add_u32 s50, s50, 0x2000
	s_addc_u32 s51, s51, 0
	v_add_f32_dpp v236, v236, v236 row_half_mirror row_mask:0xf bank_mask:0xf
	s_nop 1
	v_add_f32_dpp v236, v236, v236 row_mirror row_mask:0xf bank_mask:0xf
	s_mov_b64 exec, s[48:49]
	global_store_dword v249, v236, s[34:35] offset:3584
	s_mov_b64 exec, -1
	s_waitcnt vmcnt(63) lgkmcnt(0)
	v_pk_add_f32 v[110:111], v[238:239], v[110:111]
	v_pk_add_f32 v[112:113], v[240:241], v[112:113]
	v_pk_mul_f32 v[242:243], v[110:111], v[110:111]
	v_pk_mul_f32 v[244:245], v[112:113], v[112:113]
	v_add_f32_e32 v246, v242, v243
	v_add_f32_e32 v246, v244, v246
	v_add_f32_e32 v246, v245, v246
	global_store_dwordx4 v247, v[110:113], s[38:39]
	v_cvt_pk_bf16_f32 v242, v110, v111
	v_cvt_pk_bf16_f32 v243, v112, v113
	v_add_f32_dpp v246, v246, v246 quad_perm:[1,0,3,2] row_mask:0xf bank_mask:0xf
	global_store_dwordx2 v248, v[242:243], s[50:51]
	s_add_u32 s38, s38, 0x4000
	s_addc_u32 s39, s39, 0
	v_add_f32_dpp v246, v246, v246 quad_perm:[2,3,0,1] row_mask:0xf bank_mask:0xf
	s_add_u32 s50, s50, 0x2000
	s_addc_u32 s51, s51, 0
	v_add_f32_dpp v246, v246, v246 row_half_mirror row_mask:0xf bank_mask:0xf
	s_nop 1
	v_add_f32_dpp v246, v246, v246 row_mirror row_mask:0xf bank_mask:0xf
	s_mov_b64 exec, s[48:49]
	global_store_dword v249, v246, s[34:35] offset:3840
	s_mov_b64 exec, -1
	s_waitcnt lgkmcnt(0)
	s_branch .LBB0_1677
